# plus: nt cache policy on the once-read streaming loads of the row / weight-conversion passes (P0, P1 tail, P5, P8)
# speedup vs baseline: 1.0165x; 1.0050x over previous
.LBB0_16:
	s_mul_hi_i32 s2, s20, 0x2e8ba2e9
	s_mul_hi_i32 s3, s12, 0x2e8ba2e9
	s_lshr_b32 s4, s2, 31
	s_ashr_i32 s2, s2, 5
	s_lshr_b32 s5, s3, 31
	s_ashr_i32 s3, s3, 6
	s_add_i32 s4, s2, s4
	s_add_i32 s2, s3, s5
	s_mul_i32 s3, s2, 0x160
	s_lshl_b32 s2, s4, 6
	s_mul_i32 s5, s4, 0x2c0000
	s_sub_i32 s4, s12, s3
	s_ashr_i32 s3, s2, 31
	s_lshl_b32 s4, s4, 5
	s_mul_hi_i32 s6, s2, 0xb000
	s_add_u32 s21, s24, s5
	s_addc_u32 s22, s25, s6
	s_ashr_i32 s5, s4, 31
	s_lshl_b64 s[6:7], s[4:5], 2
	s_add_u32 s6, s21, s6
	s_addc_u32 s7, s22, s7
	s_lshl_b64 s[4:5], s[4:5], 12
	s_add_u32 s4, s10, s4
	s_addc_u32 s5, s11, s5
	s_lshl_b64 s[2:3], s[2:3], 1
	s_add_u32 s2, s4, s2
	v_lshl_add_u64 v[2:3], s[6:7], 0, v[42:43]
	s_addc_u32 s3, s5, s3
	s_add_i32 s4, s12, 1
	v_lshl_add_u64 v[14:15], v[2:3], 0, v[44:45]
	s_mul_hi_i32 s5, s4, 0x2e8ba2e9
	v_add_co_u32_e32 v18, vcc, s14, v14
	v_lshl_add_u64 v[60:61], s[2:3], 0, v[52:53]
	s_lshr_b32 s2, s5, 31
	s_ashr_i32 s3, s5, 6
	v_addc_co_u32_e32 v19, vcc, 0, v15, vcc
	s_add_i32 s3, s3, s2
	v_add_co_u32_e32 v20, vcc, s15, v14
	s_mul_i32 s5, s3, 0x160
	s_nop 0
	v_addc_co_u32_e32 v21, vcc, 0, v15, vcc
	s_lshl_b32 s2, s3, 6
	s_sub_i32 s4, s4, s5
	v_lshl_add_u64 v[4:5], s[6:7], 0, v[46:47]
	v_lshl_add_u64 v[6:7], s[6:7], 0, v[48:49]
	v_lshl_add_u64 v[8:9], s[6:7], 0, v[50:51]
	v_add_co_u32_e32 v22, vcc, s16, v14
	s_mul_i32 s6, s3, 0x2c0000
	s_ashr_i32 s3, s2, 31
	s_lshl_b32 s4, s4, 5
	v_addc_co_u32_e32 v23, vcc, 0, v15, vcc
	s_mul_hi_i32 s5, s2, 0xb000
	s_add_u32 s21, s24, s6
	v_add_co_u32_e32 v24, vcc, s17, v14
	s_addc_u32 s22, s25, s5
	s_ashr_i32 s5, s4, 31
	v_lshl_add_u64 v[2:3], v[4:5], 0, v[44:45]
	v_lshl_add_u64 v[4:5], v[6:7], 0, v[44:45]
	v_lshl_add_u64 v[16:17], v[8:9], 0, v[44:45]
	v_addc_co_u32_e32 v25, vcc, 0, v15, vcc
	s_lshl_b64 s[6:7], s[4:5], 2
	global_load_dwordx4 v[10:13], v[14:15], off nt
	global_load_dwordx4 v[6:9], v[2:3], off nt
	s_nop 0
	global_load_dwordx4 v[2:5], v[4:5], off nt
	s_add_u32 s6, s21, s6
	global_load_dwordx4 v[14:17], v[16:17], off nt
	s_nop 0
	global_load_dwordx4 v[26:29], v[18:19], off nt
	s_nop 0
	global_load_dwordx4 v[18:21], v[20:21], off nt
	s_nop 0
	global_load_dwordx4 v[30:33], v[22:23], off nt
	s_nop 0
	global_load_dwordx4 v[22:25], v[24:25], off nt
	s_addc_u32 s7, s22, s7
	v_lshl_add_u64 v[62:63], s[6:7], 0, v[42:43]
	v_lshl_add_u64 v[62:63], v[62:63], 0, v[44:45]
	v_add_co_u32_e32 v102, vcc, s14, v62
	v_lshl_add_u64 v[64:65], s[6:7], 0, v[46:47]
	s_nop 0
	v_addc_co_u32_e32 v103, vcc, 0, v63, vcc
	v_add_co_u32_e32 v106, vcc, s15, v62
	v_lshl_add_u64 v[66:67], s[6:7], 0, v[48:49]
	s_nop 0
	v_addc_co_u32_e32 v107, vcc, 0, v63, vcc
	v_add_co_u32_e32 v110, vcc, s16, v62
	v_lshl_add_u64 v[68:69], s[6:7], 0, v[50:51]
	s_nop 0
	v_addc_co_u32_e32 v111, vcc, 0, v63, vcc
	v_add_co_u32_e32 v114, vcc, s17, v62
	v_lshl_add_u64 v[64:65], v[64:65], 0, v[44:45]
	s_nop 0
	v_addc_co_u32_e32 v115, vcc, 0, v63, vcc
	v_lshl_add_u64 v[66:67], v[66:67], 0, v[44:45]
	v_lshl_add_u64 v[68:69], v[68:69], 0, v[44:45]
	global_load_dwordx4 v[86:89], v[62:63], off nt
	global_load_dwordx4 v[90:93], v[64:65], off nt
	global_load_dwordx4 v[94:97], v[66:67], off nt
	global_load_dwordx4 v[98:101], v[68:69], off nt
	s_nop 0
	global_load_dwordx4 v[102:105], v[102:103], off nt
	s_nop 0
	global_load_dwordx4 v[106:109], v[106:107], off nt
	s_nop 0
	global_load_dwordx4 v[110:113], v[110:111], off nt
	s_nop 0
	global_load_dwordx4 v[114:117], v[114:115], off nt
	v_lshl_add_u64 v[54:55], v[60:61], 0, v[34:35]
	v_lshl_add_u64 v[56:57], v[60:61], 0, v[36:37]
	s_waitcnt vmcnt(15)
	ds_write2_b32 v70, v10, v11 offset1:1
	ds_write2_b32 v70, v12, v13 offset0:2 offset1:3
	s_waitcnt vmcnt(14)
	ds_write2_b32 v71, v6, v7 offset1:1
	ds_write2_b32 v72, v8, v9 offset1:1
	s_waitcnt vmcnt(13)
	ds_write2_b32 v73, v2, v3 offset1:1
	ds_write2_b32 v74, v4, v5 offset1:1
	s_waitcnt vmcnt(12)
	ds_write2_b32 v75, v14, v15 offset1:1
	ds_write2_b32 v76, v16, v17 offset1:1
	s_waitcnt vmcnt(11)
	ds_write2_b32 v77, v26, v27 offset1:1
	ds_write2_b32 v78, v28, v29 offset1:1
	s_waitcnt vmcnt(10)
	ds_write2_b32 v79, v18, v19 offset1:1
	ds_write2_b32 v80, v20, v21 offset1:1
	s_waitcnt vmcnt(9)
	ds_write2_b32 v81, v30, v31 offset1:1
	ds_write2_b32 v82, v32, v33 offset1:1
	s_waitcnt vmcnt(8)
	ds_write2_b32 v83, v22, v23 offset1:1
	ds_write2_b32 v84, v24, v25 offset1:1
	s_waitcnt lgkmcnt(0)
	ds_read2_b32 v[2:3], v1 offset1:8
	ds_read2_b32 v[4:5], v1 offset0:33 offset1:41
	ds_read2_b32 v[6:7], v1 offset0:66 offset1:74
	ds_read2_b32 v[8:9], v1 offset0:99 offset1:107
	ds_read2_b32 v[10:11], v1 offset0:132 offset1:140
	ds_read2_b32 v[12:13], v1 offset0:165 offset1:173
	ds_read2_b32 v[14:15], v1 offset0:198 offset1:206
	ds_read2_b32 v[16:17], v1 offset0:231 offset1:239
	ds_read2_b32 v[18:19], v1 offset0:16 offset1:24
	ds_read2_b32 v[20:21], v1 offset0:49 offset1:57
	ds_read2_b32 v[22:23], v1 offset0:82 offset1:90
	ds_read2_b32 v[24:25], v1 offset0:115 offset1:123
	ds_read2_b32 v[26:27], v1 offset0:148 offset1:156
	ds_read2_b32 v[28:29], v1 offset0:181 offset1:189
	ds_read2_b32 v[30:31], v1 offset0:214 offset1:222
	ds_read2_b32 v[32:33], v1 offset0:247 offset1:255
	s_waitcnt lgkmcnt(14)
	v_bfe_u32 v85, v2, 16, 1
	s_waitcnt lgkmcnt(13)
	v_bfe_u32 v119, v6, 16, 1
	s_waitcnt lgkmcnt(11)
	v_bfe_u32 v121, v10, 16, 1
	s_waitcnt lgkmcnt(9)
	v_bfe_u32 v123, v14, 16, 1
	v_bfe_u32 v118, v4, 16, 1
	v_bfe_u32 v120, v8, 16, 1
	v_bfe_u32 v122, v12, 16, 1
	s_waitcnt lgkmcnt(8)
	v_bfe_u32 v124, v16, 16, 1
	v_bfe_u32 v125, v3, 16, 1
	v_bfe_u32 v126, v5, 16, 1
	v_bfe_u32 v127, v7, 16, 1
	v_bfe_u32 v128, v9, 16, 1
	v_bfe_u32 v129, v11, 16, 1
	v_bfe_u32 v130, v13, 16, 1
	v_bfe_u32 v131, v15, 16, 1
	v_bfe_u32 v132, v17, 16, 1
	s_waitcnt lgkmcnt(7)
	v_bfe_u32 v133, v18, 16, 1
	s_waitcnt lgkmcnt(6)
	v_bfe_u32 v134, v20, 16, 1
	s_waitcnt lgkmcnt(5)
	v_bfe_u32 v135, v22, 16, 1
	s_waitcnt lgkmcnt(4)
	v_bfe_u32 v136, v24, 16, 1
	s_waitcnt lgkmcnt(3)
	v_bfe_u32 v137, v26, 16, 1
	s_waitcnt lgkmcnt(2)
	v_bfe_u32 v138, v28, 16, 1
	s_waitcnt lgkmcnt(1)
	v_bfe_u32 v139, v30, 16, 1
	v_bfe_u32 v141, v19, 16, 1
	v_bfe_u32 v143, v23, 16, 1
	v_bfe_u32 v145, v27, 16, 1
	v_bfe_u32 v147, v31, 16, 1
	v_add3_u32 v2, v2, v85, s18
	v_add3_u32 v6, v6, v119, s18
	v_add3_u32 v10, v10, v121, s18
	v_add3_u32 v14, v14, v123, s18
	s_waitcnt lgkmcnt(0)
	v_bfe_u32 v140, v32, 16, 1
	v_bfe_u32 v142, v21, 16, 1
	v_bfe_u32 v144, v25, 16, 1
	v_bfe_u32 v146, v29, 16, 1
	v_bfe_u32 v148, v33, 16, 1
	v_add3_u32 v4, v4, v118, s18
	v_add3_u32 v8, v8, v120, s18
	v_add3_u32 v12, v12, v122, s18
	v_add3_u32 v16, v16, v124, s18
	v_add3_u32 v3, v3, v125, s18
	v_add3_u32 v85, v5, v126, s18
	v_add3_u32 v5, v7, v127, s18
	v_add3_u32 v7, v9, v128, s18
	v_add3_u32 v9, v11, v129, s18
	v_add3_u32 v11, v13, v130, s18
	v_add3_u32 v13, v15, v131, s18
	v_add3_u32 v15, v17, v132, s18
	v_add3_u32 v17, v18, v133, s18
	v_add3_u32 v18, v20, v134, s18
	v_add3_u32 v20, v22, v135, s18
	v_add3_u32 v22, v24, v136, s18
	v_add3_u32 v24, v26, v137, s18
	v_add3_u32 v26, v28, v138, s18
	v_add3_u32 v28, v30, v139, s18
	v_add3_u32 v19, v19, v141, s18
	v_add3_u32 v23, v23, v143, s18
	v_add3_u32 v27, v27, v145, s18
	v_add3_u32 v31, v31, v147, s18
	v_lshrrev_b32_e32 v2, 16, v2
	v_lshrrev_b32_e32 v6, 16, v6
	v_lshrrev_b32_e32 v10, 16, v10
	v_lshrrev_b32_e32 v14, 16, v14
	v_add3_u32 v30, v32, v140, s18
	v_add3_u32 v21, v21, v142, s18
	v_add3_u32 v25, v25, v144, s18
	v_add3_u32 v29, v29, v146, s18
	v_add3_u32 v32, v33, v148, s18
	v_lshrrev_b32_e32 v33, 16, v3
	v_lshrrev_b32_e32 v118, 16, v5
	v_lshrrev_b32_e32 v9, 16, v9
	v_lshrrev_b32_e32 v13, 16, v13
	v_lshrrev_b32_e32 v17, 16, v17
	v_lshrrev_b32_e32 v20, 16, v20
	v_lshrrev_b32_e32 v24, 16, v24
	v_lshrrev_b32_e32 v28, 16, v28
	v_lshrrev_b32_e32 v19, 16, v19
	v_lshrrev_b32_e32 v23, 16, v23
	v_lshrrev_b32_e32 v27, 16, v27
	v_lshrrev_b32_e32 v31, 16, v31
	v_and_or_b32 v2, v4, s19, v2
	v_and_or_b32 v3, v8, s19, v6
	v_and_or_b32 v4, v12, s19, v10
	v_and_or_b32 v5, v16, s19, v14
	v_lshl_add_u64 v[58:59], v[60:61], 0, v[38:39]
	v_lshl_add_u64 v[60:61], v[60:61], 0, v[40:41]
	v_and_or_b32 v6, v85, s19, v33
	v_and_or_b32 v7, v7, s19, v118
	v_and_or_b32 v8, v11, s19, v9
	v_and_or_b32 v9, v15, s19, v13
	v_and_or_b32 v10, v18, s19, v17
	v_and_or_b32 v11, v22, s19, v20
	v_and_or_b32 v12, v26, s19, v24
	v_and_or_b32 v13, v30, s19, v28
	v_and_or_b32 v14, v21, s19, v19
	v_and_or_b32 v15, v25, s19, v23
	v_and_or_b32 v16, v29, s19, v27
	v_and_or_b32 v17, v32, s19, v31
	global_store_dwordx4 v[54:55], v[2:5], off
	global_store_dwordx4 v[56:57], v[6:9], off
	global_store_dwordx4 v[58:59], v[10:13], off
	global_store_dwordx4 v[60:61], v[14:17], off
	s_waitcnt lgkmcnt(0)
	s_waitcnt vmcnt(11)
	ds_write2_b32 v70, v86, v87 offset1:1
	ds_write2_b32 v70, v88, v89 offset0:2 offset1:3
	s_waitcnt vmcnt(10)
	ds_write2_b32 v71, v90, v91 offset1:1
	ds_write2_b32 v72, v92, v93 offset1:1
	s_waitcnt vmcnt(9)
	ds_write2_b32 v73, v94, v95 offset1:1
	ds_write2_b32 v74, v96, v97 offset1:1
	s_waitcnt vmcnt(8)
	ds_write2_b32 v75, v98, v99 offset1:1
	ds_write2_b32 v76, v100, v101 offset1:1
	s_waitcnt vmcnt(7)
	ds_write2_b32 v77, v102, v103 offset1:1
	ds_write2_b32 v78, v104, v105 offset1:1
	s_waitcnt vmcnt(6)
	ds_write2_b32 v79, v106, v107 offset1:1
	ds_write2_b32 v80, v108, v109 offset1:1
	s_waitcnt vmcnt(5)
	ds_write2_b32 v81, v110, v111 offset1:1
	ds_write2_b32 v82, v112, v113 offset1:1
	s_waitcnt vmcnt(4)
	ds_write2_b32 v83, v114, v115 offset1:1
	ds_write2_b32 v84, v116, v117 offset1:1
	s_waitcnt lgkmcnt(0)
	s_lshl_b64 s[4:5], s[4:5], 12
	ds_read2_b32 v[2:3], v1 offset0:33 offset1:41
	ds_read2_b32 v[4:5], v1 offset1:8
	ds_read2_b32 v[6:7], v1 offset0:66 offset1:74
	ds_read2_b32 v[8:9], v1 offset0:99 offset1:107
	ds_read2_b32 v[10:11], v1 offset0:132 offset1:140
	ds_read2_b32 v[12:13], v1 offset0:165 offset1:173
	ds_read2_b32 v[14:15], v1 offset0:198 offset1:206
	ds_read2_b32 v[16:17], v1 offset0:231 offset1:239
	ds_read2_b32 v[18:19], v1 offset0:49 offset1:57
	ds_read2_b32 v[20:21], v1 offset0:16 offset1:24
	ds_read2_b32 v[22:23], v1 offset0:82 offset1:90
	ds_read2_b32 v[24:25], v1 offset0:115 offset1:123
	ds_read2_b32 v[26:27], v1 offset0:148 offset1:156
	ds_read2_b32 v[28:29], v1 offset0:181 offset1:189
	ds_read2_b32 v[30:31], v1 offset0:214 offset1:222
	ds_read2_b32 v[32:33], v1 offset0:247 offset1:255
	s_add_u32 s4, s10, s4
	s_addc_u32 s5, s11, s5
	s_lshl_b64 s[2:3], s[2:3], 1
	s_add_u32 s2, s4, s2
	s_waitcnt lgkmcnt(14)
	v_bfe_u32 v54, v4, 16, 1
	v_bfe_u32 v57, v3, 16, 1
	s_waitcnt lgkmcnt(13)
	v_bfe_u32 v58, v6, 16, 1
	v_bfe_u32 v59, v7, 16, 1
	s_waitcnt lgkmcnt(12)
	v_bfe_u32 v60, v8, 16, 1
	v_bfe_u32 v61, v9, 16, 1
	s_waitcnt lgkmcnt(11)
	v_bfe_u32 v85, v10, 16, 1
	v_bfe_u32 v86, v11, 16, 1
	s_waitcnt lgkmcnt(10)
	v_bfe_u32 v87, v12, 16, 1
	v_bfe_u32 v88, v13, 16, 1
	s_waitcnt lgkmcnt(9)
	v_bfe_u32 v89, v14, 16, 1
	s_addc_u32 s3, s5, s3
	v_bfe_u32 v55, v5, 16, 1
	v_bfe_u32 v56, v2, 16, 1
	v_bfe_u32 v90, v15, 16, 1
	s_waitcnt lgkmcnt(8)
	v_bfe_u32 v91, v16, 16, 1
	v_bfe_u32 v92, v17, 16, 1
	s_waitcnt lgkmcnt(6)
	v_bfe_u32 v93, v20, 16, 1
	v_bfe_u32 v94, v21, 16, 1
	s_waitcnt lgkmcnt(5)
	v_bfe_u32 v97, v22, 16, 1
	v_bfe_u32 v98, v23, 16, 1
	s_waitcnt lgkmcnt(4)
	v_bfe_u32 v99, v24, 16, 1
	v_bfe_u32 v100, v25, 16, 1
	s_waitcnt lgkmcnt(3)
	v_bfe_u32 v101, v26, 16, 1
	v_bfe_u32 v102, v27, 16, 1
	s_waitcnt lgkmcnt(2)
	v_bfe_u32 v103, v28, 16, 1
	v_bfe_u32 v104, v29, 16, 1
	s_waitcnt lgkmcnt(1)
	v_bfe_u32 v105, v30, 16, 1
	v_bfe_u32 v106, v31, 16, 1
	v_add3_u32 v4, v4, v54, s18
	v_add3_u32 v54, v3, v57, s18
	v_add3_u32 v3, v6, v58, s18
	v_add3_u32 v6, v7, v59, s18
	v_add3_u32 v7, v8, v60, s18
	v_add3_u32 v8, v9, v61, s18
	v_add3_u32 v9, v10, v85, s18
	v_add3_u32 v10, v11, v86, s18
	v_add3_u32 v11, v12, v87, s18
	v_add3_u32 v12, v13, v88, s18
	v_add3_u32 v13, v14, v89, s18
	v_lshl_add_u64 v[68:69], s[2:3], 0, v[52:53]
	v_bfe_u32 v95, v18, 16, 1
	v_bfe_u32 v96, v19, 16, 1
	s_waitcnt lgkmcnt(0)
	v_bfe_u32 v107, v32, 16, 1
	v_bfe_u32 v108, v33, 16, 1
	v_add3_u32 v5, v5, v55, s18
	v_add3_u32 v2, v2, v56, s18
	v_add3_u32 v14, v15, v90, s18
	v_add3_u32 v15, v16, v91, s18
	v_add3_u32 v16, v17, v92, s18
	v_add3_u32 v17, v20, v93, s18
	v_add3_u32 v20, v21, v94, s18
	v_add3_u32 v21, v22, v97, s18
	v_add3_u32 v22, v23, v98, s18
	v_add3_u32 v23, v24, v99, s18
	v_add3_u32 v24, v25, v100, s18
	v_add3_u32 v25, v26, v101, s18
	v_add3_u32 v26, v27, v102, s18
	v_add3_u32 v27, v28, v103, s18
	v_add3_u32 v28, v29, v104, s18
	v_add3_u32 v29, v30, v105, s18
	v_add3_u32 v30, v31, v106, s18
	v_lshrrev_b32_e32 v4, 16, v4
	v_lshrrev_b32_e32 v3, 16, v3
	v_lshrrev_b32_e32 v9, 16, v9
	v_lshrrev_b32_e32 v13, 16, v13
	v_lshl_add_u64 v[62:63], v[68:69], 0, v[34:35]
	v_add3_u32 v18, v18, v95, s18
	v_add3_u32 v19, v19, v96, s18
	v_add3_u32 v31, v32, v107, s18
	v_add3_u32 v32, v33, v108, s18
	v_lshrrev_b32_e32 v33, 16, v5
	v_lshrrev_b32_e32 v55, 16, v6
	v_lshrrev_b32_e32 v10, 16, v10
	v_lshrrev_b32_e32 v14, 16, v14
	v_lshrrev_b32_e32 v17, 16, v17
	v_lshrrev_b32_e32 v21, 16, v21
	v_lshrrev_b32_e32 v25, 16, v25
	v_lshrrev_b32_e32 v29, 16, v29
	v_lshrrev_b32_e32 v20, 16, v20
	v_lshrrev_b32_e32 v22, 16, v22
	v_lshrrev_b32_e32 v26, 16, v26
	v_lshrrev_b32_e32 v30, 16, v30
	v_and_or_b32 v2, v2, s19, v4
	v_and_or_b32 v3, v7, s19, v3
	v_and_or_b32 v4, v11, s19, v9
	v_and_or_b32 v5, v15, s19, v13
	v_lshl_add_u64 v[64:65], v[68:69], 0, v[36:37]
	v_lshl_add_u64 v[66:67], v[68:69], 0, v[38:39]
	v_lshl_add_u64 v[68:69], v[68:69], 0, v[40:41]
	v_and_or_b32 v6, v54, s19, v33
	v_and_or_b32 v7, v8, s19, v55
	v_and_or_b32 v8, v12, s19, v10
	v_and_or_b32 v9, v16, s19, v14
	v_and_or_b32 v10, v18, s19, v17
	v_and_or_b32 v11, v23, s19, v21
	v_and_or_b32 v12, v27, s19, v25
	v_and_or_b32 v13, v31, s19, v29
	v_and_or_b32 v14, v19, s19, v20
	v_and_or_b32 v15, v24, s19, v22
	v_and_or_b32 v16, v28, s19, v26
	v_and_or_b32 v17, v32, s19, v30
	global_store_dwordx4 v[62:63], v[2:5], off
	global_store_dwordx4 v[64:65], v[6:9], off
	global_store_dwordx4 v[66:67], v[10:13], off
	global_store_dwordx4 v[68:69], v[14:17], off
	s_waitcnt lgkmcnt(0)
	s_add_i32 s20, s20, s8
	s_add_i32 s12, s12, s13
	s_cmpk_gt_i32 s20, 0x15ff
	s_cbranch_scc0 .LBB0_16

.LBB0_29:
	s_cmp_lg_u64 s[2:3], 0
	s_cselect_b64 s[16:17], -1, 0
	s_cmp_eq_u64 s[2:3], 0
	v_lshl_add_u64 v[4:5], s[2:3], 0, v[72:73]
	v_mov_b32_e32 v50, 0
	v_mov_b32_e32 v62, 0
	v_mov_b32_e32 v63, 0
	v_mov_b32_e32 v64, 0
	v_mov_b32_e32 v65, 0
	s_cbranch_scc1 .LBB0_31
	global_load_dwordx4 v[62:65], v[4:5], off nt
.LBB0_31:
	s_cmp_lg_u64 s[4:5], 0
	s_cselect_b64 s[18:19], -1, 0
	s_cmp_eq_u64 s[4:5], 0
	v_lshl_add_u64 v[66:67], s[4:5], 0, v[72:73]
	v_mov_b32_e32 v51, 0
	v_mov_b32_e32 v52, 0
	v_mov_b32_e32 v53, 0
	s_cbranch_scc1 .LBB0_33
	global_load_dwordx4 v[50:53], v[66:67], off nt
.LBB0_33:
	v_cndmask_b32_e64 v2, 0, 1, s[16:17]
	v_mov_b32_e32 v42, 0
	v_cmp_ne_u32_e64 s[4:5], 1, v2
	s_andn2_b64 vcc, exec, s[16:17]
	v_mov_b32_e32 v89, 0
	v_mov_b32_e32 v59, 0
	v_mov_b32_e32 v87, 0
	v_mov_b32_e32 v61, 0
	s_cbranch_vccnz .LBB0_35
	global_load_dwordx4 v[58:61], v[4:5], off offset:1024 nt
	s_waitcnt vmcnt(0)
	v_mov_b32_e32 v89, v58
	v_mov_b32_e32 v87, v60
.LBB0_35:
	v_cndmask_b32_e64 v2, 0, 1, s[18:19]
	v_cmp_ne_u32_e64 s[2:3], 1, v2
	s_andn2_b64 vcc, exec, s[18:19]
	v_mov_b32_e32 v43, 0
	v_mov_b32_e32 v44, 0
	v_mov_b32_e32 v45, 0
	s_cbranch_vccnz .LBB0_37
	global_load_dwordx4 v[42:45], v[66:67], off offset:1024 nt
.LBB0_37:
	v_mov_b32_e32 v30, 0
	s_and_b64 vcc, exec, s[4:5]
	v_mov_b32_e32 v54, 0
	v_mov_b32_e32 v55, 0
	v_mov_b32_e32 v56, 0
	v_mov_b32_e32 v57, 0
	s_cbranch_vccnz .LBB0_39
	global_load_dwordx4 v[54:57], v[4:5], off offset:2048 nt
.LBB0_39:
	s_and_b64 vcc, exec, s[2:3]
	v_mov_b32_e32 v31, 0
	v_mov_b32_e32 v32, 0
	v_mov_b32_e32 v33, 0
	s_cbranch_vccnz .LBB0_41
	global_load_dwordx4 v[30:33], v[66:67], off offset:2048 nt
.LBB0_41:
	v_mov_b32_e32 v18, 0
	s_and_b64 vcc, exec, s[4:5]
	v_mov_b32_e32 v46, 0
	v_mov_b32_e32 v47, 0
	v_mov_b32_e32 v48, 0
	v_mov_b32_e32 v49, 0
	s_cbranch_vccnz .LBB0_43
	global_load_dwordx4 v[46:49], v[4:5], off offset:3072 nt
.LBB0_43:
	s_and_b64 vcc, exec, s[2:3]
	v_mov_b32_e32 v19, 0
	v_mov_b32_e32 v20, 0
	v_mov_b32_e32 v21, 0
	s_cbranch_vccnz .LBB0_45
	global_load_dwordx4 v[18:21], v[66:67], off offset:3072 nt
.LBB0_45:
	v_mov_b32_e32 v14, 0
	s_and_b64 vcc, exec, s[4:5]
	v_mov_b32_e32 v38, 0
	v_mov_b32_e32 v39, 0
	v_mov_b32_e32 v40, 0
	v_mov_b32_e32 v41, 0
	s_cbranch_vccnz .LBB0_47
	v_add_co_u32_e32 v2, vcc, 0x1000, v4
	s_nop 1
	v_addc_co_u32_e32 v3, vcc, 0, v5, vcc
	global_load_dwordx4 v[38:41], v[2:3], off nt
.LBB0_47:
	s_and_b64 vcc, exec, s[2:3]
	v_mov_b32_e32 v15, 0
	v_mov_b32_e32 v16, 0
	v_mov_b32_e32 v17, 0
	s_cbranch_vccnz .LBB0_49
	v_add_co_u32_e32 v2, vcc, 0x1000, v66
	s_nop 1
	v_addc_co_u32_e32 v3, vcc, 0, v67, vcc
	global_load_dwordx4 v[14:17], v[2:3], off nt
.LBB0_49:
	v_mov_b32_e32 v10, 0
	s_and_b64 vcc, exec, s[4:5]
	v_mov_b32_e32 v34, 0
	v_mov_b32_e32 v35, 0
	v_mov_b32_e32 v36, 0
	v_mov_b32_e32 v37, 0
	s_cbranch_vccnz .LBB0_51
	v_add_co_u32_e32 v2, vcc, 0x1000, v4
	s_nop 1
	v_addc_co_u32_e32 v3, vcc, 0, v5, vcc
	global_load_dwordx4 v[34:37], v[2:3], off offset:1024 nt
.LBB0_51:
	s_and_b64 vcc, exec, s[2:3]
	v_mov_b32_e32 v11, 0
	v_mov_b32_e32 v12, 0
	v_mov_b32_e32 v13, 0
	s_cbranch_vccnz .LBB0_53
	v_add_co_u32_e32 v2, vcc, 0x1000, v66
	s_nop 1
	v_addc_co_u32_e32 v3, vcc, 0, v67, vcc
	global_load_dwordx4 v[10:13], v[2:3], off offset:1024 nt
.LBB0_53:
	v_mov_b32_e32 v6, 0
	s_and_b64 vcc, exec, s[4:5]
	v_mov_b32_e32 v26, 0
	v_mov_b32_e32 v27, 0
	v_mov_b32_e32 v28, 0
	v_mov_b32_e32 v29, 0
	s_cbranch_vccnz .LBB0_55
	v_add_co_u32_e32 v2, vcc, 0x1000, v4
	s_nop 1
	v_addc_co_u32_e32 v3, vcc, 0, v5, vcc
	global_load_dwordx4 v[26:29], v[2:3], off offset:2048 nt
.LBB0_55:
	s_and_b64 vcc, exec, s[2:3]
	v_mov_b32_e32 v7, 0
	v_mov_b32_e32 v8, 0
	v_mov_b32_e32 v9, 0
	s_cbranch_vccnz .LBB0_57
	v_add_co_u32_e32 v2, vcc, 0x1000, v66
	s_nop 1
	v_addc_co_u32_e32 v3, vcc, 0, v67, vcc
	global_load_dwordx4 v[6:9], v[2:3], off offset:2048 nt
.LBB0_57:
	v_mov_b32_e32 v2, 0
	s_and_b64 vcc, exec, s[4:5]
	v_mov_b32_e32 v22, 0
	v_mov_b32_e32 v23, 0
	v_mov_b32_e32 v24, 0
	v_mov_b32_e32 v25, 0
	s_cbranch_vccnz .LBB0_59
	v_add_co_u32_e32 v4, vcc, 0x1000, v4
	s_nop 1
	v_addc_co_u32_e32 v5, vcc, 0, v5, vcc
	global_load_dwordx4 v[22:25], v[4:5], off offset:3072 nt
.LBB0_59:
	s_and_b64 vcc, exec, s[2:3]
	v_mov_b32_e32 v3, 0
	v_mov_b32_e32 v4, 0
	v_mov_b32_e32 v5, 0
	s_cbranch_vccnz .LBB0_61
	v_add_co_u32_e32 v2, vcc, 0x1000, v66
	s_nop 1
	v_addc_co_u32_e32 v3, vcc, 0, v67, vcc
	global_load_dwordx4 v[2:5], v[2:3], off offset:3072 nt

.LBB0_514:
	v_mul_u32_u24_e32 v2, s24, v1
	v_mul_u32_u24_e32 v4, s24, v91
	v_mul_u32_u24_e32 v22, s24, v92
	v_mul_u32_u24_e32 v24, s24, v93
	v_mul_u32_u24_e32 v42, s24, v77
	v_mul_u32_u24_e32 v44, s24, v88
	v_mul_u32_u24_e32 v58, s24, v89
	v_mul_u32_u24_e32 v60, s24, v90
	v_lshlrev_b32_e32 v2, 2, v2
	v_mov_b32_e32 v3, v75
	v_lshlrev_b32_e32 v4, 2, v4
	v_mov_b32_e32 v5, v75
	v_lshlrev_b32_e32 v22, 2, v22
	v_mov_b32_e32 v23, v75
	v_lshlrev_b32_e32 v24, 2, v24
	v_mov_b32_e32 v25, v75
	v_lshlrev_b32_e32 v42, 2, v42
	v_mov_b32_e32 v43, v75
	v_lshlrev_b32_e32 v44, 2, v44
	v_mov_b32_e32 v45, v75
	v_lshlrev_b32_e32 v58, 2, v58
	v_mov_b32_e32 v59, v75
	v_lshlrev_b32_e32 v60, 2, v60
	v_mov_b32_e32 v61, v75
	v_lshl_add_u64 v[2:3], s[22:23], 0, v[2:3]
	v_mov_b32_e32 v87, v75
	v_lshl_add_u64 v[4:5], s[22:23], 0, v[4:5]
	v_lshl_add_u64 v[22:23], s[22:23], 0, v[22:23]
	v_lshl_add_u64 v[24:25], s[22:23], 0, v[24:25]
	v_lshl_add_u64 v[42:43], s[22:23], 0, v[42:43]
	v_lshl_add_u64 v[44:45], s[22:23], 0, v[44:45]
	v_lshl_add_u64 v[58:59], s[22:23], 0, v[58:59]
	v_lshl_add_u64 v[60:61], s[22:23], 0, v[60:61]
	v_lshl_add_u64 v[2:3], v[2:3], 0, v[86:87]
	v_lshl_add_u64 v[10:11], v[4:5], 0, v[86:87]
	v_lshl_add_u64 v[22:23], v[22:23], 0, v[86:87]
	v_lshl_add_u64 v[26:27], v[24:25], 0, v[86:87]
	v_lshl_add_u64 v[42:43], v[42:43], 0, v[86:87]
	v_lshl_add_u64 v[46:47], v[44:45], 0, v[86:87]
	v_lshl_add_u64 v[58:59], v[58:59], 0, v[86:87]
	v_lshl_add_u64 v[62:63], v[60:61], 0, v[86:87]
	global_load_dwordx4 v[2:5], v[2:3], off nt
	s_nop 0
	global_load_dwordx4 v[10:13], v[10:11], off nt
	s_nop 0
	global_load_dwordx4 v[22:25], v[22:23], off nt
	s_nop 0
	global_load_dwordx4 v[26:29], v[26:27], off nt
	s_nop 0
	global_load_dwordx4 v[42:45], v[42:43], off nt
	s_nop 0
	global_load_dwordx4 v[46:49], v[46:47], off nt
	s_nop 0
	global_load_dwordx4 v[58:61], v[58:59], off nt
	s_nop 0
	global_load_dwordx4 v[62:65], v[62:63], off nt
	s_waitcnt vmcnt(19)
	ds_write2_b32 v95, v14, v15 offset1:1
	ds_write2_b32 v95, v16, v17 offset0:2 offset1:3
	s_waitcnt vmcnt(18)
	ds_write2_b32 v96, v6, v7 offset1:1
	ds_write2_b32 v97, v8, v9 offset1:1
	s_waitcnt vmcnt(17)
	ds_write2_b32 v98, v30, v31 offset1:1
	ds_write2_b32 v99, v32, v33 offset1:1
	s_waitcnt vmcnt(16)
	ds_write2_b32 v100, v18, v19 offset1:1
	ds_write2_b32 v101, v20, v21 offset1:1
	s_waitcnt vmcnt(15)
	ds_write2_b32 v102, v38, v39 offset1:1
	ds_write2_b32 v103, v40, v41 offset1:1
	s_waitcnt vmcnt(14)
	ds_write2_b32 v104, v34, v35 offset1:1
	ds_write2_b32 v105, v36, v37 offset1:1
	s_waitcnt vmcnt(13)
	ds_write2_b32 v106, v54, v55 offset1:1
	ds_write2_b32 v107, v56, v57 offset1:1
	s_waitcnt vmcnt(12)
	ds_write2_b32 v108, v50, v51 offset1:1
	ds_write2_b32 v109, v52, v53 offset1:1
	s_waitcnt lgkmcnt(0)
	ds_read2_b32 v[14:15], v94 offset1:8
	ds_read2_b32 v[18:19], v94 offset0:33 offset1:41
	ds_read2_b32 v[20:21], v94 offset0:66 offset1:74
	ds_read2_b32 v[30:31], v94 offset0:99 offset1:107
	ds_read2_b32 v[32:33], v94 offset0:132 offset1:140
	s_waitcnt lgkmcnt(4)
	v_bfe_u32 v6, v14, 16, 1
	v_add3_u32 v6, v14, v6, s28
	s_waitcnt lgkmcnt(3)
	v_bfe_u32 v7, v18, 16, 1
	v_lshrrev_b32_e32 v6, 16, v6
	v_add3_u32 v7, v18, v7, s28
	ds_read2_b32 v[34:35], v94 offset0:165 offset1:173
	v_and_or_b32 v6, v7, s29, v6
	s_waitcnt lgkmcnt(3)
	v_bfe_u32 v7, v20, 16, 1
	v_add3_u32 v7, v20, v7, s28
	s_waitcnt lgkmcnt(2)
	v_bfe_u32 v8, v30, 16, 1
	ds_read2_b32 v[36:37], v94 offset0:198 offset1:206
	v_lshrrev_b32_e32 v7, 16, v7
	v_add3_u32 v8, v30, v8, s28
	ds_read2_b32 v[38:39], v94 offset0:231 offset1:239
	s_lshl_b64 s[16:17], s[16:17], 12
	v_and_or_b32 v7, v8, s29, v7
	s_waitcnt lgkmcnt(3)
	v_bfe_u32 v8, v32, 16, 1
	s_add_u32 s20, s20, s16
	v_add3_u32 v8, v32, v8, s28
	s_waitcnt lgkmcnt(2)
	v_bfe_u32 v9, v34, 16, 1
	s_addc_u32 s21, s21, s17
	s_lshl_b64 s[16:17], s[0:1], 1
	v_lshrrev_b32_e32 v8, 16, v8
	v_add3_u32 v9, v34, v9, s28
	s_add_u32 s16, s20, s16
	v_and_or_b32 v8, v9, s29, v8
	s_waitcnt lgkmcnt(1)
	v_bfe_u32 v9, v36, 16, 1
	s_addc_u32 s17, s21, s17
	v_add3_u32 v9, v36, v9, s28
	s_waitcnt lgkmcnt(0)
	v_bfe_u32 v14, v38, 16, 1
	v_lshl_add_u64 v[16:17], s[16:17], 0, v[74:75]
	v_lshrrev_b32_e32 v9, 16, v9
	v_add3_u32 v14, v38, v14, s28
	v_and_or_b32 v9, v14, s29, v9
	v_lshl_add_u64 v[40:41], v[16:17], 0, v[78:79]
	global_store_dwordx4 v[40:41], v[6:9], off
	v_bfe_u32 v14, v39, 16, 1
	v_add3_u32 v18, v39, v14, s28
	v_bfe_u32 v6, v15, 16, 1
	v_add3_u32 v6, v15, v6, s28
	v_bfe_u32 v7, v19, 16, 1
	v_lshrrev_b32_e32 v6, 16, v6
	v_add3_u32 v7, v19, v7, s28
	v_and_or_b32 v6, v7, s29, v6
	v_bfe_u32 v7, v21, 16, 1
	v_add3_u32 v7, v21, v7, s28
	v_bfe_u32 v8, v31, 16, 1
	v_lshrrev_b32_e32 v7, 16, v7
	v_add3_u32 v8, v31, v8, s28
	v_and_or_b32 v7, v8, s29, v7
	v_bfe_u32 v8, v33, 16, 1
	v_add3_u32 v8, v33, v8, s28
	v_bfe_u32 v9, v35, 16, 1
	v_lshrrev_b32_e32 v8, 16, v8
	v_add3_u32 v9, v35, v9, s28
	v_and_or_b32 v8, v9, s29, v8
	v_bfe_u32 v9, v37, 16, 1
	v_add3_u32 v9, v37, v9, s28
	v_lshrrev_b32_e32 v9, 16, v9
	ds_read2_b32 v[14:15], v94 offset0:16 offset1:24
	v_and_or_b32 v9, v18, s29, v9
	v_lshl_add_u64 v[18:19], v[16:17], 0, v[80:81]
	global_store_dwordx4 v[18:19], v[6:9], off
	ds_read2_b32 v[18:19], v94 offset0:49 offset1:57
	ds_read2_b32 v[20:21], v94 offset0:82 offset1:90
	ds_read2_b32 v[30:31], v94 offset0:115 offset1:123
	s_waitcnt lgkmcnt(3)
	v_bfe_u32 v6, v14, 16, 1
	v_add3_u32 v6, v14, v6, s28
	s_waitcnt lgkmcnt(2)
	v_bfe_u32 v7, v18, 16, 1
	ds_read2_b32 v[32:33], v94 offset0:148 offset1:156
	v_lshrrev_b32_e32 v6, 16, v6
	v_add3_u32 v7, v18, v7, s28
	ds_read2_b32 v[34:35], v94 offset0:181 offset1:189
	v_and_or_b32 v6, v7, s29, v6
	s_waitcnt lgkmcnt(3)
	v_bfe_u32 v7, v20, 16, 1
	v_add3_u32 v7, v20, v7, s28
	s_waitcnt lgkmcnt(2)
	v_bfe_u32 v8, v30, 16, 1
	ds_read2_b32 v[36:37], v94 offset0:214 offset1:222
	v_lshrrev_b32_e32 v7, 16, v7
	v_add3_u32 v8, v30, v8, s28
	ds_read2_b32 v[38:39], v94 offset0:247 offset1:255
	v_and_or_b32 v7, v8, s29, v7
	s_waitcnt lgkmcnt(3)
	v_bfe_u32 v8, v32, 16, 1
	v_add3_u32 v8, v32, v8, s28
	s_waitcnt lgkmcnt(2)
	v_bfe_u32 v9, v34, 16, 1
	v_lshrrev_b32_e32 v8, 16, v8
	v_add3_u32 v9, v34, v9, s28
	v_and_or_b32 v8, v9, s29, v8
	s_waitcnt lgkmcnt(1)
	v_bfe_u32 v9, v36, 16, 1
	v_add3_u32 v9, v36, v9, s28
	s_waitcnt lgkmcnt(0)
	v_bfe_u32 v14, v38, 16, 1
	v_lshrrev_b32_e32 v9, 16, v9
	v_add3_u32 v14, v38, v14, s28
	v_and_or_b32 v9, v14, s29, v9
	v_lshl_add_u64 v[40:41], v[16:17], 0, v[82:83]
	global_store_dwordx4 v[40:41], v[6:9], off
	v_bfe_u32 v14, v39, 16, 1
	v_add3_u32 v14, v39, v14, s28
	v_bfe_u32 v6, v15, 16, 1
	v_add3_u32 v6, v15, v6, s28
	v_bfe_u32 v7, v19, 16, 1
	v_lshrrev_b32_e32 v6, 16, v6
	v_add3_u32 v7, v19, v7, s28
	v_and_or_b32 v6, v7, s29, v6
	v_bfe_u32 v7, v21, 16, 1
	v_add3_u32 v7, v21, v7, s28
	v_bfe_u32 v8, v31, 16, 1
	v_lshrrev_b32_e32 v7, 16, v7
	v_add3_u32 v8, v31, v8, s28
	v_and_or_b32 v7, v8, s29, v7
	v_bfe_u32 v8, v33, 16, 1
	v_add3_u32 v8, v33, v8, s28
	v_bfe_u32 v9, v35, 16, 1
	v_lshrrev_b32_e32 v8, 16, v8
	v_add3_u32 v9, v35, v9, s28
	v_and_or_b32 v8, v9, s29, v8
	v_bfe_u32 v9, v37, 16, 1
	v_add3_u32 v9, v37, v9, s28
	v_lshrrev_b32_e32 v9, 16, v9
	v_and_or_b32 v9, v14, s29, v9
	v_lshl_add_u64 v[14:15], v[16:17], 0, v[84:85]
	global_store_dwordx4 v[14:15], v[6:9], off
	s_waitcnt lgkmcnt(0)
	s_waitcnt vmcnt(11)
	ds_write2_b32 v95, v2, v3 offset1:1
	ds_write2_b32 v95, v4, v5 offset0:2 offset1:3
	s_waitcnt vmcnt(10)
	ds_write2_b32 v96, v10, v11 offset1:1
	ds_write2_b32 v97, v12, v13 offset1:1
	s_waitcnt vmcnt(9)
	ds_write2_b32 v98, v22, v23 offset1:1
	ds_write2_b32 v99, v24, v25 offset1:1
	s_waitcnt vmcnt(8)
	ds_write2_b32 v100, v26, v27 offset1:1
	ds_write2_b32 v101, v28, v29 offset1:1
	s_waitcnt vmcnt(7)
	ds_write2_b32 v102, v42, v43 offset1:1
	ds_write2_b32 v103, v44, v45 offset1:1
	s_waitcnt vmcnt(6)
	ds_write2_b32 v104, v46, v47 offset1:1
	ds_write2_b32 v105, v48, v49 offset1:1
	s_waitcnt vmcnt(5)
	ds_write2_b32 v106, v58, v59 offset1:1
	ds_write2_b32 v107, v60, v61 offset1:1
	s_waitcnt vmcnt(4)
	ds_write2_b32 v108, v62, v63 offset1:1
	ds_write2_b32 v109, v64, v65 offset1:1
	s_waitcnt lgkmcnt(0)
	ds_read2_b32 v[6:7], v94 offset1:8
	ds_read2_b32 v[10:11], v94 offset0:33 offset1:41
	ds_read2_b32 v[12:13], v94 offset0:66 offset1:74
	ds_read2_b32 v[14:15], v94 offset0:99 offset1:107
	ds_read2_b32 v[16:17], v94 offset0:132 offset1:140
	s_waitcnt lgkmcnt(4)
	v_bfe_u32 v2, v6, 16, 1
	v_add3_u32 v2, v6, v2, s28
	s_waitcnt lgkmcnt(3)
	v_bfe_u32 v3, v10, 16, 1
	v_lshrrev_b32_e32 v2, 16, v2
	v_add3_u32 v3, v10, v3, s28
	ds_read2_b32 v[18:19], v94 offset0:165 offset1:173
	v_and_or_b32 v2, v3, s29, v2
	s_waitcnt lgkmcnt(3)
	v_bfe_u32 v3, v12, 16, 1
	v_add3_u32 v3, v12, v3, s28
	s_waitcnt lgkmcnt(2)
	v_bfe_u32 v4, v14, 16, 1
	ds_read2_b32 v[20:21], v94 offset0:198 offset1:206
	v_lshrrev_b32_e32 v3, 16, v3
	v_add3_u32 v4, v14, v4, s28
	ds_read2_b32 v[22:23], v94 offset0:231 offset1:239
	s_lshl_b64 s[14:15], s[14:15], 12
	v_and_or_b32 v3, v4, s29, v3
	s_waitcnt lgkmcnt(3)
	v_bfe_u32 v4, v16, 16, 1
	s_add_u32 s0, s18, s14
	v_add3_u32 v4, v16, v4, s28
	s_waitcnt lgkmcnt(2)
	v_bfe_u32 v5, v18, 16, 1
	s_addc_u32 s14, s19, s15
	s_lshl_b64 s[6:7], s[6:7], 1
	v_lshrrev_b32_e32 v4, 16, v4
	v_add3_u32 v5, v18, v5, s28
	s_add_u32 s6, s0, s6
	v_and_or_b32 v4, v5, s29, v4
	s_waitcnt lgkmcnt(1)
	v_bfe_u32 v5, v20, 16, 1
	s_addc_u32 s7, s14, s7
	v_add3_u32 v5, v20, v5, s28
	s_waitcnt lgkmcnt(0)
	v_bfe_u32 v6, v22, 16, 1
	v_lshl_add_u64 v[8:9], s[6:7], 0, v[74:75]
	v_lshrrev_b32_e32 v5, 16, v5
	v_add3_u32 v6, v22, v6, s28
	v_and_or_b32 v5, v6, s29, v5
	v_lshl_add_u64 v[24:25], v[8:9], 0, v[78:79]
	global_store_dwordx4 v[24:25], v[2:5], off
	v_bfe_u32 v6, v23, 16, 1
	v_add3_u32 v10, v23, v6, s28
	v_bfe_u32 v2, v7, 16, 1
	v_add3_u32 v2, v7, v2, s28
	v_bfe_u32 v3, v11, 16, 1
	v_lshrrev_b32_e32 v2, 16, v2
	v_add3_u32 v3, v11, v3, s28
	v_and_or_b32 v2, v3, s29, v2
	v_bfe_u32 v3, v13, 16, 1
	v_add3_u32 v3, v13, v3, s28
	v_bfe_u32 v4, v15, 16, 1
	v_lshrrev_b32_e32 v3, 16, v3
	v_add3_u32 v4, v15, v4, s28
	v_and_or_b32 v3, v4, s29, v3
	v_bfe_u32 v4, v17, 16, 1
	v_add3_u32 v4, v17, v4, s28
	v_bfe_u32 v5, v19, 16, 1
	v_lshrrev_b32_e32 v4, 16, v4
	v_add3_u32 v5, v19, v5, s28
	v_and_or_b32 v4, v5, s29, v4
	v_bfe_u32 v5, v21, 16, 1
	v_add3_u32 v5, v21, v5, s28
	v_lshrrev_b32_e32 v5, 16, v5
	ds_read2_b32 v[6:7], v94 offset0:16 offset1:24
	v_and_or_b32 v5, v10, s29, v5
	v_lshl_add_u64 v[10:11], v[8:9], 0, v[80:81]
	global_store_dwordx4 v[10:11], v[2:5], off
	ds_read2_b32 v[10:11], v94 offset0:49 offset1:57
	ds_read2_b32 v[12:13], v94 offset0:82 offset1:90
	ds_read2_b32 v[14:15], v94 offset0:115 offset1:123
	s_waitcnt lgkmcnt(3)
	v_bfe_u32 v2, v6, 16, 1
	v_add3_u32 v2, v6, v2, s28
	s_waitcnt lgkmcnt(2)
	v_bfe_u32 v3, v10, 16, 1
	ds_read2_b32 v[16:17], v94 offset0:148 offset1:156
	v_lshrrev_b32_e32 v2, 16, v2
	v_add3_u32 v3, v10, v3, s28
	ds_read2_b32 v[18:19], v94 offset0:181 offset1:189
	v_and_or_b32 v2, v3, s29, v2
	s_waitcnt lgkmcnt(3)
	v_bfe_u32 v3, v12, 16, 1
	v_add3_u32 v3, v12, v3, s28
	s_waitcnt lgkmcnt(2)
	v_bfe_u32 v4, v14, 16, 1
	ds_read2_b32 v[20:21], v94 offset0:214 offset1:222
	v_lshrrev_b32_e32 v3, 16, v3
	v_add3_u32 v4, v14, v4, s28
	ds_read2_b32 v[22:23], v94 offset0:247 offset1:255
	v_and_or_b32 v3, v4, s29, v3
	s_waitcnt lgkmcnt(3)
	v_bfe_u32 v4, v16, 16, 1
	v_add3_u32 v4, v16, v4, s28
	s_waitcnt lgkmcnt(2)
	v_bfe_u32 v5, v18, 16, 1
	v_lshrrev_b32_e32 v4, 16, v4
	v_add3_u32 v5, v18, v5, s28
	v_and_or_b32 v4, v5, s29, v4
	s_waitcnt lgkmcnt(1)
	v_bfe_u32 v5, v20, 16, 1
	v_add3_u32 v5, v20, v5, s28
	s_waitcnt lgkmcnt(0)
	v_bfe_u32 v6, v22, 16, 1
	v_lshrrev_b32_e32 v5, 16, v5
	v_add3_u32 v6, v22, v6, s28
	v_and_or_b32 v5, v6, s29, v5
	v_lshl_add_u64 v[24:25], v[8:9], 0, v[82:83]
	global_store_dwordx4 v[24:25], v[2:5], off
	v_bfe_u32 v6, v23, 16, 1
	v_add3_u32 v6, v23, v6, s28
	v_bfe_u32 v2, v7, 16, 1
	v_add3_u32 v2, v7, v2, s28
	v_bfe_u32 v3, v11, 16, 1
	v_lshrrev_b32_e32 v2, 16, v2
	v_add3_u32 v3, v11, v3, s28
	v_and_or_b32 v2, v3, s29, v2
	v_bfe_u32 v3, v13, 16, 1
	v_add3_u32 v3, v13, v3, s28
	v_bfe_u32 v4, v15, 16, 1
	v_lshrrev_b32_e32 v3, 16, v3
	v_add3_u32 v4, v15, v4, s28
	v_and_or_b32 v3, v4, s29, v3
	v_bfe_u32 v4, v17, 16, 1
	v_add3_u32 v4, v17, v4, s28
	v_bfe_u32 v5, v19, 16, 1
	v_lshrrev_b32_e32 v4, 16, v4
	v_add3_u32 v5, v19, v5, s28
	v_and_or_b32 v4, v5, s29, v4
	v_bfe_u32 v5, v21, 16, 1
	v_add3_u32 v5, v21, v5, s28
	v_lshrrev_b32_e32 v5, 16, v5
	v_and_or_b32 v5, v6, s29, v5
	v_lshl_add_u64 v[6:7], v[8:9], 0, v[84:85]
	global_store_dwordx4 v[6:7], v[2:5], off
	s_waitcnt lgkmcnt(0)
	s_mov_b64 s[6:7], 0

.LBB0_533:
	v_mul_u32_u24_e32 v2, s14, v1
	v_lshlrev_b32_e32 v74, 2, v2
	v_mul_u32_u24_e32 v4, s14, v91
	v_lshl_add_u64 v[2:3], s[6:7], 0, v[74:75]
	v_mov_b32_e32 v87, v75
	v_lshlrev_b32_e32 v74, 2, v4
	v_lshl_add_u64 v[2:3], v[2:3], 0, v[86:87]
	v_lshl_add_u64 v[4:5], s[6:7], 0, v[74:75]
	v_lshl_add_u64 v[4:5], v[4:5], 0, v[86:87]
	global_load_dwordx4 v[22:25], v[2:3], off nt
	global_load_dwordx4 v[18:21], v[4:5], off nt
	v_mul_u32_u24_e32 v2, s14, v92
	v_lshlrev_b32_e32 v74, 2, v2
	v_mul_u32_u24_e32 v4, s14, v93
	v_lshl_add_u64 v[2:3], s[6:7], 0, v[74:75]
	v_lshlrev_b32_e32 v74, 2, v4
	v_lshl_add_u64 v[2:3], v[2:3], 0, v[86:87]
	v_lshl_add_u64 v[4:5], s[6:7], 0, v[74:75]
	v_lshl_add_u64 v[4:5], v[4:5], 0, v[86:87]
	global_load_dwordx4 v[38:41], v[2:3], off nt
	global_load_dwordx4 v[34:37], v[4:5], off nt
	v_mul_u32_u24_e32 v2, s14, v77
	v_lshlrev_b32_e32 v74, 2, v2
	v_mul_u32_u24_e32 v4, s14, v88
	v_lshl_add_u64 v[2:3], s[6:7], 0, v[74:75]
	v_lshlrev_b32_e32 v74, 2, v4
	v_lshl_add_u64 v[2:3], v[2:3], 0, v[86:87]
	v_lshl_add_u64 v[4:5], s[6:7], 0, v[74:75]
	v_lshl_add_u64 v[4:5], v[4:5], 0, v[86:87]
	global_load_dwordx4 v[54:57], v[2:3], off nt
	global_load_dwordx4 v[50:53], v[4:5], off nt
	v_mul_u32_u24_e32 v2, s14, v89
	v_lshlrev_b32_e32 v74, 2, v2
	v_mul_u32_u24_e32 v4, s14, v90
	v_lshl_add_u64 v[2:3], s[6:7], 0, v[74:75]
	v_lshlrev_b32_e32 v74, 2, v4
	v_lshl_add_u64 v[2:3], v[2:3], 0, v[86:87]
	v_lshl_add_u64 v[4:5], s[6:7], 0, v[74:75]
	v_lshl_add_u64 v[4:5], v[4:5], 0, v[86:87]
	global_load_dwordx4 v[62:65], v[2:3], off nt
	global_load_dwordx4 v[58:61], v[4:5], off nt
	s_add_i32 s31, s30, 1
	s_cmpk_gt_u32 s30, 0x3fe
	s_mov_b64 s[26:27], -1
	s_cbranch_scc0 .LBB0_543
	s_cmpk_gt_u32 s30, 0x7fe
	s_cbranch_scc0 .LBB0_540
	s_cmpk_gt_u32 s30, 0xffe
	s_mov_b64 s[18:19], -1
	s_cbranch_scc0 .LBB0_537
	s_add_i32 s6, s31, 0xf000
	s_and_b32 s7, s6, 0xffff
	s_mul_i32 s7, s7, 0xba2f
	s_lshr_b32 s15, s7, 24
	s_mul_i32 s7, s15, 0x160
	s_sub_i32 s18, s6, s7
	s_lshl_b32 s6, s18, 5
	s_and_b32 s7, s18, 0xffff
	s_add_i32 s14, s6, 0xea00
	s_cmpk_gt_u32 s7, 0xaf
	s_cselect_b32 s6, s14, s6
	s_sext_i32_i16 s7, s6
	s_cselect_b32 s14, 0x80, 0
	s_bfe_u32 s7, s7, 0x70018
	s_add_i32 s7, s6, s7
	s_sext_i32_i16 s19, s7
	s_and_b32 s7, s7, 0xff80
	s_sub_i32 s6, s6, s7
	s_lshl_b32 s19, s19, 1
	s_sext_i32_i16 s6, s6
	s_and_b32 s19, s19, 0xffffff00
	s_add_i32 s6, s14, s6
	s_add_i32 s14, s6, s19
	s_lshl_b32 s6, s15, 6
	s_mul_i32 s15, s15, 0x2c0000
	s_add_u32 s15, s84, s15
	s_addc_u32 s19, s85, 0
	s_lshl_b32 s18, s18, 7
	s_and_b32 s18, s18, 0x3ff80
	s_add_u32 s22, s15, s18
	s_mov_b32 s7, s1
	s_addc_u32 s23, s19, 0
	s_ashr_i32 s15, s14, 31
	s_mov_b64 s[18:19], 0

.LBB0_545:
	v_mul_u32_u24_e32 v2, s24, v1
	v_lshlrev_b32_e32 v74, 2, v2
	v_mul_u32_u24_e32 v4, s24, v91
	v_lshl_add_u64 v[2:3], s[22:23], 0, v[74:75]
	v_lshlrev_b32_e32 v74, 2, v4
	v_mul_u32_u24_e32 v10, s24, v92
	v_lshl_add_u64 v[4:5], s[22:23], 0, v[74:75]
	v_lshlrev_b32_e32 v74, 2, v10
	v_mul_u32_u24_e32 v12, s24, v93
	v_lshl_add_u64 v[10:11], s[22:23], 0, v[74:75]
	v_lshlrev_b32_e32 v74, 2, v12
	v_mul_u32_u24_e32 v26, s24, v77
	v_lshl_add_u64 v[12:13], s[22:23], 0, v[74:75]
	v_lshlrev_b32_e32 v74, 2, v26
	v_mul_u32_u24_e32 v28, s24, v88
	v_lshl_add_u64 v[26:27], s[22:23], 0, v[74:75]
	v_lshlrev_b32_e32 v74, 2, v28
	v_mul_u32_u24_e32 v42, s24, v89
	v_lshl_add_u64 v[28:29], s[22:23], 0, v[74:75]
	v_lshlrev_b32_e32 v74, 2, v42
	v_mul_u32_u24_e32 v44, s24, v90
	v_lshl_add_u64 v[42:43], s[22:23], 0, v[74:75]
	v_lshlrev_b32_e32 v74, 2, v44
	v_mov_b32_e32 v87, v75
	v_lshl_add_u64 v[44:45], s[22:23], 0, v[74:75]
	v_lshl_add_u64 v[2:3], v[2:3], 0, v[86:87]
	v_lshl_add_u64 v[4:5], v[4:5], 0, v[86:87]
	v_lshl_add_u64 v[10:11], v[10:11], 0, v[86:87]
	v_lshl_add_u64 v[12:13], v[12:13], 0, v[86:87]
	v_lshl_add_u64 v[26:27], v[26:27], 0, v[86:87]
	v_lshl_add_u64 v[28:29], v[28:29], 0, v[86:87]
	v_lshl_add_u64 v[42:43], v[42:43], 0, v[86:87]
	v_lshl_add_u64 v[44:45], v[44:45], 0, v[86:87]
	global_load_dwordx4 v[6:9], v[2:3], off nt
	s_nop 0
	global_load_dwordx4 v[2:5], v[4:5], off nt
	s_nop 0
	global_load_dwordx4 v[14:17], v[10:11], off nt
	s_nop 0
	global_load_dwordx4 v[10:13], v[12:13], off nt
	s_nop 0
	global_load_dwordx4 v[30:33], v[26:27], off nt
	s_nop 0
	global_load_dwordx4 v[26:29], v[28:29], off nt
	s_nop 0
	global_load_dwordx4 v[46:49], v[42:43], off nt
	s_nop 0
	global_load_dwordx4 v[42:45], v[44:45], off nt
	v_add_u32_e32 v96, 0x420, v95
	v_add_u32_e32 v97, 0x428, v95
	v_add_u32_e32 v98, 0x840, v95
	v_add_u32_e32 v99, 0x848, v95
	v_add_u32_e32 v100, 0xc60, v95
	v_add_u32_e32 v101, 0xc68, v95
	v_add_u32_e32 v102, 0x1080, v95
	v_add_u32_e32 v103, 0x1088, v95
	v_add_u32_e32 v104, 0x14a0, v95
	v_add_u32_e32 v105, 0x14a8, v95
	v_add_u32_e32 v106, 0x18c0, v95
	v_add_u32_e32 v107, 0x18c8, v95
	v_add_u32_e32 v108, 0x1ce0, v95
	v_add_u32_e32 v109, 0x1ce8, v95
	s_waitcnt vmcnt(0)
	ds_write2_b32 v95, v22, v23 offset1:1
	ds_write2_b32 v95, v24, v25 offset0:2 offset1:3
	ds_write2_b32 v96, v18, v19 offset1:1
	ds_write2_b32 v97, v20, v21 offset1:1
	ds_write2_b32 v98, v38, v39 offset1:1
	ds_write2_b32 v99, v40, v41 offset1:1
	ds_write2_b32 v100, v34, v35 offset1:1
	ds_write2_b32 v101, v36, v37 offset1:1
	ds_write2_b32 v102, v54, v55 offset1:1
	ds_write2_b32 v103, v56, v57 offset1:1
	ds_write2_b32 v104, v50, v51 offset1:1
	ds_write2_b32 v105, v52, v53 offset1:1
	ds_write2_b32 v106, v62, v63 offset1:1
	ds_write2_b32 v107, v64, v65 offset1:1
	ds_write2_b32 v108, v58, v59 offset1:1
	ds_write2_b32 v109, v60, v61 offset1:1
	s_waitcnt lgkmcnt(0)
	ds_read2_b32 v[22:23], v94 offset1:8
	ds_read2_b32 v[34:35], v94 offset0:33 offset1:41
	ds_read2_b32 v[36:37], v94 offset0:66 offset1:74
	ds_read2_b32 v[38:39], v94 offset0:99 offset1:107
	ds_read2_b32 v[40:41], v94 offset0:132 offset1:140
	s_waitcnt lgkmcnt(4)
	v_bfe_u32 v18, v22, 16, 1
	v_add3_u32 v18, v22, v18, s28
	s_waitcnt lgkmcnt(3)
	v_bfe_u32 v19, v34, 16, 1
	v_lshrrev_b32_e32 v18, 16, v18
	v_add3_u32 v19, v34, v19, s28
	ds_read2_b32 v[50:51], v94 offset0:165 offset1:173
	v_and_or_b32 v18, v19, s29, v18
	s_waitcnt lgkmcnt(3)
	v_bfe_u32 v19, v36, 16, 1
	v_add3_u32 v19, v36, v19, s28
	s_waitcnt lgkmcnt(2)
	v_bfe_u32 v20, v38, 16, 1
	ds_read2_b32 v[52:53], v94 offset0:198 offset1:206
	v_lshrrev_b32_e32 v19, 16, v19
	v_add3_u32 v20, v38, v20, s28
	ds_read2_b32 v[54:55], v94 offset0:231 offset1:239
	s_lshl_b64 s[16:17], s[16:17], 12
	v_and_or_b32 v19, v20, s29, v19
	s_waitcnt lgkmcnt(3)
	v_bfe_u32 v20, v40, 16, 1
	s_add_u32 s20, s20, s16
	v_add3_u32 v20, v40, v20, s28
	s_waitcnt lgkmcnt(2)
	v_bfe_u32 v21, v50, 16, 1
	s_addc_u32 s21, s21, s17
	s_lshl_b64 s[16:17], s[0:1], 1
	v_lshrrev_b32_e32 v20, 16, v20
	v_add3_u32 v21, v50, v21, s28
	s_add_u32 s16, s20, s16
	v_and_or_b32 v20, v21, s29, v20
	s_waitcnt lgkmcnt(1)
	v_bfe_u32 v21, v52, 16, 1
	s_addc_u32 s17, s21, s17
	v_lshlrev_b32_e32 v74, 1, v76
	v_add3_u32 v21, v52, v21, s28
	s_waitcnt lgkmcnt(0)
	v_bfe_u32 v22, v54, 16, 1
	v_lshl_add_u64 v[24:25], s[16:17], 0, v[74:75]
	v_lshrrev_b32_e32 v21, 16, v21
	v_add3_u32 v22, v54, v22, s28
	v_and_or_b32 v21, v22, s29, v21
	v_lshl_add_u64 v[56:57], v[24:25], 0, v[78:79]
	global_store_dwordx4 v[56:57], v[18:21], off
	v_bfe_u32 v22, v55, 16, 1
	v_add3_u32 v34, v55, v22, s28
	v_bfe_u32 v18, v23, 16, 1
	v_add3_u32 v18, v23, v18, s28
	v_bfe_u32 v19, v35, 16, 1
	v_lshrrev_b32_e32 v18, 16, v18
	v_add3_u32 v19, v35, v19, s28
	v_and_or_b32 v18, v19, s29, v18
	v_bfe_u32 v19, v37, 16, 1
	v_add3_u32 v19, v37, v19, s28
	v_bfe_u32 v20, v39, 16, 1
	v_lshrrev_b32_e32 v19, 16, v19
	v_add3_u32 v20, v39, v20, s28
	v_and_or_b32 v19, v20, s29, v19
	v_bfe_u32 v20, v41, 16, 1
	v_add3_u32 v20, v41, v20, s28
	v_bfe_u32 v21, v51, 16, 1
	v_lshrrev_b32_e32 v20, 16, v20
	v_add3_u32 v21, v51, v21, s28
	v_and_or_b32 v20, v21, s29, v20
	v_bfe_u32 v21, v53, 16, 1
	v_add3_u32 v21, v53, v21, s28
	v_lshrrev_b32_e32 v21, 16, v21
	ds_read2_b32 v[22:23], v94 offset0:16 offset1:24
	v_and_or_b32 v21, v34, s29, v21
	v_lshl_add_u64 v[34:35], v[24:25], 0, v[80:81]
	global_store_dwordx4 v[34:35], v[18:21], off
	ds_read2_b32 v[34:35], v94 offset0:49 offset1:57
	ds_read2_b32 v[36:37], v94 offset0:82 offset1:90
	ds_read2_b32 v[38:39], v94 offset0:115 offset1:123
	s_waitcnt lgkmcnt(3)
	v_bfe_u32 v18, v22, 16, 1
	v_add3_u32 v18, v22, v18, s28
	s_waitcnt lgkmcnt(2)
	v_bfe_u32 v19, v34, 16, 1
	ds_read2_b32 v[40:41], v94 offset0:148 offset1:156
	v_lshrrev_b32_e32 v18, 16, v18
	v_add3_u32 v19, v34, v19, s28
	ds_read2_b32 v[50:51], v94 offset0:181 offset1:189
	v_and_or_b32 v18, v19, s29, v18
	s_waitcnt lgkmcnt(3)
	v_bfe_u32 v19, v36, 16, 1
	v_add3_u32 v19, v36, v19, s28
	s_waitcnt lgkmcnt(2)
	v_bfe_u32 v20, v38, 16, 1
	ds_read2_b32 v[52:53], v94 offset0:214 offset1:222
	v_lshrrev_b32_e32 v19, 16, v19
	v_add3_u32 v20, v38, v20, s28
	ds_read2_b32 v[54:55], v94 offset0:247 offset1:255
	v_and_or_b32 v19, v20, s29, v19
	s_waitcnt lgkmcnt(3)
	v_bfe_u32 v20, v40, 16, 1
	v_add3_u32 v20, v40, v20, s28
	s_waitcnt lgkmcnt(2)
	v_bfe_u32 v21, v50, 16, 1
	v_lshrrev_b32_e32 v20, 16, v20
	v_add3_u32 v21, v50, v21, s28
	v_and_or_b32 v20, v21, s29, v20
	s_waitcnt lgkmcnt(1)
	v_bfe_u32 v21, v52, 16, 1
	v_add3_u32 v21, v52, v21, s28
	s_waitcnt lgkmcnt(0)
	v_bfe_u32 v22, v54, 16, 1
	v_lshrrev_b32_e32 v21, 16, v21
	v_add3_u32 v22, v54, v22, s28
	v_and_or_b32 v21, v22, s29, v21
	v_lshl_add_u64 v[56:57], v[24:25], 0, v[82:83]
	global_store_dwordx4 v[56:57], v[18:21], off
	v_bfe_u32 v22, v55, 16, 1
	v_add3_u32 v22, v55, v22, s28
	v_bfe_u32 v18, v23, 16, 1
	v_add3_u32 v18, v23, v18, s28
	v_bfe_u32 v19, v35, 16, 1
	v_lshrrev_b32_e32 v18, 16, v18
	v_add3_u32 v19, v35, v19, s28
	v_and_or_b32 v18, v19, s29, v18
	v_bfe_u32 v19, v37, 16, 1
	v_add3_u32 v19, v37, v19, s28
	v_bfe_u32 v20, v39, 16, 1
	v_lshrrev_b32_e32 v19, 16, v19
	v_add3_u32 v20, v39, v20, s28
	v_and_or_b32 v19, v20, s29, v19
	v_bfe_u32 v20, v41, 16, 1
	v_add3_u32 v20, v41, v20, s28
	v_bfe_u32 v21, v51, 16, 1
	v_lshrrev_b32_e32 v20, 16, v20
	v_add3_u32 v21, v51, v21, s28
	v_and_or_b32 v20, v21, s29, v20
	v_bfe_u32 v21, v53, 16, 1
	v_add3_u32 v21, v53, v21, s28
	v_lshrrev_b32_e32 v21, 16, v21
	v_and_or_b32 v21, v22, s29, v21
	v_lshl_add_u64 v[22:23], v[24:25], 0, v[84:85]
	global_store_dwordx4 v[22:23], v[18:21], off
	s_waitcnt lgkmcnt(0)
	s_add_i32 s31, s30, 2
	s_cmpk_gt_u32 s30, 0x3fd
	s_mov_b64 s[26:27], -1
	s_cbranch_scc0 .LBB0_555
	s_cmpk_gt_u32 s30, 0x7fd
	s_cbranch_scc0 .LBB0_552
	s_cmpk_gt_u32 s30, 0xffd
	s_mov_b64 s[20:21], -1
	s_cbranch_scc0 .LBB0_549
	s_add_i32 s0, s31, 0xf000
	s_and_b32 s16, s0, 0xffff
	s_mul_i32 s16, s16, 0xba2f
	s_lshr_b32 s17, s16, 24
	s_mul_i32 s16, s17, 0x160
	s_sub_i32 s20, s0, s16
	s_lshl_b32 s0, s20, 5
	s_and_b32 s16, s20, 0xffff
	s_add_i32 s21, s0, 0xea00
	s_cmpk_gt_u32 s16, 0xaf
	s_cselect_b32 s0, s21, s0
	s_sext_i32_i16 s16, s0
	s_cselect_b32 s21, 0x80, 0
	s_bfe_u32 s16, s16, 0x70018
	s_add_i32 s16, s0, s16
	s_sext_i32_i16 s22, s16
	s_and_b32 s16, s16, 0xff80
	s_sub_i32 s0, s0, s16
	s_lshl_b32 s22, s22, 1
	s_sext_i32_i16 s0, s0
	s_and_b32 s22, s22, 0xffffff00
	s_add_i32 s0, s21, s0
	s_add_i32 s16, s0, s22
	s_lshl_b32 s0, s17, 6
	s_mul_i32 s17, s17, 0x2c0000
	s_add_u32 s17, s84, s17
	s_addc_u32 s21, s85, 0
	s_lshl_b32 s20, s20, 7
	s_and_b32 s20, s20, 0x3ff80
	s_add_u32 s22, s17, s20
	s_addc_u32 s23, s21, 0
	s_ashr_i32 s17, s16, 31
	s_mov_b64 s[20:21], 0

.LBB0_557:
	v_mul_u32_u24_e32 v18, s24, v1
	v_mul_u32_u24_e32 v20, s24, v91
	v_mul_u32_u24_e32 v34, s24, v92
	v_mul_u32_u24_e32 v36, s24, v93
	v_mul_u32_u24_e32 v50, s24, v77
	v_mul_u32_u24_e32 v52, s24, v88
	v_mul_u32_u24_e32 v58, s24, v89
	v_mul_u32_u24_e32 v60, s24, v90
	v_lshlrev_b32_e32 v18, 2, v18
	v_mov_b32_e32 v19, v75
	v_lshlrev_b32_e32 v20, 2, v20
	v_mov_b32_e32 v21, v75
	v_lshlrev_b32_e32 v34, 2, v34
	v_mov_b32_e32 v35, v75
	v_lshlrev_b32_e32 v36, 2, v36
	v_mov_b32_e32 v37, v75
	v_lshlrev_b32_e32 v50, 2, v50
	v_mov_b32_e32 v51, v75
	v_lshlrev_b32_e32 v52, 2, v52
	v_mov_b32_e32 v53, v75
	v_lshlrev_b32_e32 v58, 2, v58
	v_mov_b32_e32 v59, v75
	v_lshlrev_b32_e32 v60, 2, v60
	v_mov_b32_e32 v61, v75
	v_lshl_add_u64 v[18:19], s[22:23], 0, v[18:19]
	v_mov_b32_e32 v87, v75
	v_lshl_add_u64 v[20:21], s[22:23], 0, v[20:21]
	v_lshl_add_u64 v[34:35], s[22:23], 0, v[34:35]
	v_lshl_add_u64 v[36:37], s[22:23], 0, v[36:37]
	v_lshl_add_u64 v[50:51], s[22:23], 0, v[50:51]
	v_lshl_add_u64 v[52:53], s[22:23], 0, v[52:53]
	v_lshl_add_u64 v[58:59], s[22:23], 0, v[58:59]
	v_lshl_add_u64 v[60:61], s[22:23], 0, v[60:61]
	v_lshl_add_u64 v[18:19], v[18:19], 0, v[86:87]
	v_lshl_add_u64 v[20:21], v[20:21], 0, v[86:87]
	v_lshl_add_u64 v[34:35], v[34:35], 0, v[86:87]
	v_lshl_add_u64 v[36:37], v[36:37], 0, v[86:87]
	v_lshl_add_u64 v[50:51], v[50:51], 0, v[86:87]
	v_lshl_add_u64 v[52:53], v[52:53], 0, v[86:87]
	v_lshl_add_u64 v[58:59], v[58:59], 0, v[86:87]
	v_lshl_add_u64 v[60:61], v[60:61], 0, v[86:87]
	global_load_dwordx4 v[22:25], v[18:19], off nt
	s_nop 0
	global_load_dwordx4 v[18:21], v[20:21], off nt
	s_nop 0
	global_load_dwordx4 v[38:41], v[34:35], off nt
	s_nop 0
	global_load_dwordx4 v[34:37], v[36:37], off nt
	s_nop 0
	global_load_dwordx4 v[54:57], v[50:51], off nt
	s_nop 0
	global_load_dwordx4 v[50:53], v[52:53], off nt
	s_nop 0
	global_load_dwordx4 v[66:69], v[58:59], off nt
	s_nop 0
	global_load_dwordx4 v[58:61], v[60:61], off nt
	ds_write2_b32 v95, v6, v7 offset1:1
	ds_write2_b32 v95, v8, v9 offset0:2 offset1:3
	ds_write2_b32 v96, v2, v3 offset1:1
	ds_write2_b32 v97, v4, v5 offset1:1
	ds_write2_b32 v98, v14, v15 offset1:1
	ds_write2_b32 v99, v16, v17 offset1:1
	ds_write2_b32 v100, v10, v11 offset1:1
	ds_write2_b32 v101, v12, v13 offset1:1
	ds_write2_b32 v102, v30, v31 offset1:1
	ds_write2_b32 v103, v32, v33 offset1:1
	ds_write2_b32 v104, v26, v27 offset1:1
	ds_write2_b32 v105, v28, v29 offset1:1
	ds_write2_b32 v106, v46, v47 offset1:1
	ds_write2_b32 v107, v48, v49 offset1:1
	ds_write2_b32 v108, v42, v43 offset1:1
	ds_write2_b32 v109, v44, v45 offset1:1
	s_waitcnt lgkmcnt(0)
	ds_read2_b32 v[6:7], v94 offset1:8
	ds_read2_b32 v[10:11], v94 offset0:33 offset1:41
	ds_read2_b32 v[12:13], v94 offset0:66 offset1:74
	ds_read2_b32 v[14:15], v94 offset0:99 offset1:107
	ds_read2_b32 v[16:17], v94 offset0:132 offset1:140
	s_waitcnt lgkmcnt(4)
	v_bfe_u32 v2, v6, 16, 1
	v_add3_u32 v2, v6, v2, s28
	s_waitcnt lgkmcnt(3)
	v_bfe_u32 v3, v10, 16, 1
	v_lshrrev_b32_e32 v2, 16, v2
	v_add3_u32 v3, v10, v3, s28
	ds_read2_b32 v[26:27], v94 offset0:165 offset1:173
	v_and_or_b32 v2, v3, s29, v2
	s_waitcnt lgkmcnt(3)
	v_bfe_u32 v3, v12, 16, 1
	v_add3_u32 v3, v12, v3, s28
	s_waitcnt lgkmcnt(2)
	v_bfe_u32 v4, v14, 16, 1
	ds_read2_b32 v[28:29], v94 offset0:198 offset1:206
	v_lshrrev_b32_e32 v3, 16, v3
	v_add3_u32 v4, v14, v4, s28
	ds_read2_b32 v[30:31], v94 offset0:231 offset1:239
	s_lshl_b64 s[14:15], s[14:15], 12
	v_and_or_b32 v3, v4, s29, v3
	s_waitcnt lgkmcnt(3)
	v_bfe_u32 v4, v16, 16, 1
	s_add_u32 s14, s18, s14
	v_add3_u32 v4, v16, v4, s28
	s_waitcnt lgkmcnt(2)
	v_bfe_u32 v5, v26, 16, 1
	s_addc_u32 s15, s19, s15
	s_lshl_b64 s[6:7], s[6:7], 1
	v_lshrrev_b32_e32 v4, 16, v4
	v_add3_u32 v5, v26, v5, s28
	s_add_u32 s6, s14, s6
	v_and_or_b32 v4, v5, s29, v4
	s_waitcnt lgkmcnt(1)
	v_bfe_u32 v5, v28, 16, 1
	s_addc_u32 s7, s15, s7
	v_add3_u32 v5, v28, v5, s28
	s_waitcnt lgkmcnt(0)
	v_bfe_u32 v6, v30, 16, 1
	v_lshl_add_u64 v[8:9], s[6:7], 0, v[74:75]
	v_lshrrev_b32_e32 v5, 16, v5
	v_add3_u32 v6, v30, v6, s28
	v_and_or_b32 v5, v6, s29, v5
	v_lshl_add_u64 v[32:33], v[8:9], 0, v[78:79]
	global_store_dwordx4 v[32:33], v[2:5], off
	v_bfe_u32 v6, v31, 16, 1
	v_add3_u32 v10, v31, v6, s28
	v_bfe_u32 v2, v7, 16, 1
	v_add3_u32 v2, v7, v2, s28
	v_bfe_u32 v3, v11, 16, 1
	v_lshrrev_b32_e32 v2, 16, v2
	v_add3_u32 v3, v11, v3, s28
	v_and_or_b32 v2, v3, s29, v2
	v_bfe_u32 v3, v13, 16, 1
	v_add3_u32 v3, v13, v3, s28
	v_bfe_u32 v4, v15, 16, 1
	v_lshrrev_b32_e32 v3, 16, v3
	v_add3_u32 v4, v15, v4, s28
	v_and_or_b32 v3, v4, s29, v3
	v_bfe_u32 v4, v17, 16, 1
	v_add3_u32 v4, v17, v4, s28
	v_bfe_u32 v5, v27, 16, 1
	v_lshrrev_b32_e32 v4, 16, v4
	v_add3_u32 v5, v27, v5, s28
	v_and_or_b32 v4, v5, s29, v4
	v_bfe_u32 v5, v29, 16, 1
	v_add3_u32 v5, v29, v5, s28
	v_lshrrev_b32_e32 v5, 16, v5
	ds_read2_b32 v[6:7], v94 offset0:16 offset1:24
	v_and_or_b32 v5, v10, s29, v5
	v_lshl_add_u64 v[10:11], v[8:9], 0, v[80:81]
	global_store_dwordx4 v[10:11], v[2:5], off
	ds_read2_b32 v[10:11], v94 offset0:49 offset1:57
	ds_read2_b32 v[12:13], v94 offset0:82 offset1:90
	ds_read2_b32 v[14:15], v94 offset0:115 offset1:123
	s_waitcnt lgkmcnt(3)
	v_bfe_u32 v2, v6, 16, 1
	v_add3_u32 v2, v6, v2, s28
	s_waitcnt lgkmcnt(2)
	v_bfe_u32 v3, v10, 16, 1
	ds_read2_b32 v[16:17], v94 offset0:148 offset1:156
	v_lshrrev_b32_e32 v2, 16, v2
	v_add3_u32 v3, v10, v3, s28
	ds_read2_b32 v[26:27], v94 offset0:181 offset1:189
	v_and_or_b32 v2, v3, s29, v2
	s_waitcnt lgkmcnt(3)
	v_bfe_u32 v3, v12, 16, 1
	v_add3_u32 v3, v12, v3, s28
	s_waitcnt lgkmcnt(2)
	v_bfe_u32 v4, v14, 16, 1
	ds_read2_b32 v[28:29], v94 offset0:214 offset1:222
	v_lshrrev_b32_e32 v3, 16, v3
	v_add3_u32 v4, v14, v4, s28
	ds_read2_b32 v[30:31], v94 offset0:247 offset1:255
	v_and_or_b32 v3, v4, s29, v3
	s_waitcnt lgkmcnt(3)
	v_bfe_u32 v4, v16, 16, 1
	v_add3_u32 v4, v16, v4, s28
	s_waitcnt lgkmcnt(2)
	v_bfe_u32 v5, v26, 16, 1
	v_lshrrev_b32_e32 v4, 16, v4
	v_add3_u32 v5, v26, v5, s28
	v_and_or_b32 v4, v5, s29, v4
	s_waitcnt lgkmcnt(1)
	v_bfe_u32 v5, v28, 16, 1
	v_add3_u32 v5, v28, v5, s28
	s_waitcnt lgkmcnt(0)
	v_bfe_u32 v6, v30, 16, 1
	v_lshrrev_b32_e32 v5, 16, v5
	v_add3_u32 v6, v30, v6, s28
	v_and_or_b32 v5, v6, s29, v5
	v_lshl_add_u64 v[32:33], v[8:9], 0, v[82:83]
	global_store_dwordx4 v[32:33], v[2:5], off
	v_bfe_u32 v6, v31, 16, 1
	v_add3_u32 v6, v31, v6, s28
	v_bfe_u32 v2, v7, 16, 1
	v_add3_u32 v2, v7, v2, s28
	v_bfe_u32 v3, v11, 16, 1
	v_lshrrev_b32_e32 v2, 16, v2
	v_add3_u32 v3, v11, v3, s28
	v_and_or_b32 v2, v3, s29, v2
	v_bfe_u32 v3, v13, 16, 1
	v_add3_u32 v3, v13, v3, s28
	v_bfe_u32 v4, v15, 16, 1
	v_lshrrev_b32_e32 v3, 16, v3
	v_add3_u32 v4, v15, v4, s28
	v_and_or_b32 v3, v4, s29, v3
	v_bfe_u32 v4, v17, 16, 1
	v_add3_u32 v4, v17, v4, s28
	v_bfe_u32 v5, v27, 16, 1
	v_lshrrev_b32_e32 v4, 16, v4
	v_add3_u32 v5, v27, v5, s28
	v_and_or_b32 v4, v5, s29, v4
	v_bfe_u32 v5, v29, 16, 1
	v_add3_u32 v5, v29, v5, s28
	v_lshrrev_b32_e32 v5, 16, v5
	v_and_or_b32 v5, v6, s29, v5
	v_lshl_add_u64 v[6:7], v[8:9], 0, v[84:85]
	global_store_dwordx4 v[6:7], v[2:5], off
	s_waitcnt lgkmcnt(0)
	s_add_i32 s31, s30, 3
	s_cmpk_lt_u32 s30, 0x3fd
	s_mov_b64 s[26:27], -1
	s_cbranch_scc1 .LBB0_567
	s_cmpk_lt_u32 s30, 0x7fd
	s_cbranch_scc1 .LBB0_564
	s_cmpk_lt_u32 s30, 0xffd
	s_mov_b64 s[18:19], -1
	s_cbranch_scc1 .LBB0_561
	s_add_i32 s6, s31, 0xf000
	s_and_b32 s7, s6, 0xffff
	s_mul_i32 s7, s7, 0xba2f
	s_lshr_b32 s15, s7, 24
	s_mul_i32 s7, s15, 0x160
	s_sub_i32 s18, s6, s7
	s_lshl_b32 s6, s18, 5
	s_and_b32 s7, s18, 0xffff
	s_add_i32 s14, s6, 0xea00
	s_cmpk_gt_u32 s7, 0xaf
	s_cselect_b32 s6, s14, s6
	s_sext_i32_i16 s7, s6
	s_cselect_b32 s14, 0x80, 0
	s_bfe_u32 s7, s7, 0x70018
	s_add_i32 s7, s6, s7
	s_sext_i32_i16 s19, s7
	s_and_b32 s7, s7, 0xff80
	s_sub_i32 s6, s6, s7
	s_lshl_b32 s19, s19, 1
	s_sext_i32_i16 s6, s6
	s_and_b32 s19, s19, 0xffffff00
	s_add_i32 s6, s14, s6
	s_add_i32 s14, s6, s19
	s_lshl_b32 s6, s15, 6
	s_mul_i32 s15, s15, 0x2c0000
	s_add_u32 s15, s84, s15
	s_addc_u32 s19, s85, 0
	s_lshl_b32 s18, s18, 7
	s_and_b32 s18, s18, 0x3ff80
	s_add_u32 s22, s15, s18
	s_mov_b32 s7, s1
	s_addc_u32 s23, s19, 0
	s_ashr_i32 s15, s14, 31
	s_mov_b64 s[18:19], 0

.LBB0_569:
	v_mul_u32_u24_e32 v2, s24, v1
	v_mul_u32_u24_e32 v4, s24, v91
	v_mul_u32_u24_e32 v6, s24, v92
	v_lshlrev_b32_e32 v2, 2, v2
	v_mov_b32_e32 v3, v75
	v_lshlrev_b32_e32 v4, 2, v4
	v_mov_b32_e32 v5, v75
	v_lshlrev_b32_e32 v6, 2, v6
	v_mov_b32_e32 v7, v75
	v_mul_u32_u24_e32 v8, s24, v93
	v_lshl_add_u64 v[2:3], s[22:23], 0, v[2:3]
	v_mov_b32_e32 v87, v75
	v_lshl_add_u64 v[4:5], s[22:23], 0, v[4:5]
	v_lshl_add_u64 v[6:7], s[22:23], 0, v[6:7]
	v_lshlrev_b32_e32 v8, 2, v8
	v_mov_b32_e32 v9, v75
	v_lshl_add_u64 v[2:3], v[2:3], 0, v[86:87]
	v_lshl_add_u64 v[4:5], v[4:5], 0, v[86:87]
	v_lshl_add_u64 v[6:7], v[6:7], 0, v[86:87]
	v_lshl_add_u64 v[8:9], s[22:23], 0, v[8:9]
	global_load_dwordx4 v[10:13], v[2:3], off nt
	s_nop 0
	global_load_dwordx4 v[2:5], v[4:5], off nt
	v_lshl_add_u64 v[8:9], v[8:9], 0, v[86:87]
	global_load_dwordx4 v[30:33], v[6:7], off nt
	global_load_dwordx4 v[26:29], v[8:9], off nt
	v_mul_u32_u24_e32 v6, s24, v77
	v_lshlrev_b32_e32 v6, 2, v6
	v_mov_b32_e32 v7, v75
	v_mul_u32_u24_e32 v8, s24, v88
	v_lshl_add_u64 v[6:7], s[22:23], 0, v[6:7]
	v_lshlrev_b32_e32 v8, 2, v8
	v_mov_b32_e32 v9, v75
	v_lshl_add_u64 v[6:7], v[6:7], 0, v[86:87]
	v_lshl_add_u64 v[8:9], s[22:23], 0, v[8:9]
	v_lshl_add_u64 v[8:9], v[8:9], 0, v[86:87]
	global_load_dwordx4 v[46:49], v[6:7], off nt
	global_load_dwordx4 v[42:45], v[8:9], off nt
	v_mul_u32_u24_e32 v6, s24, v89
	v_lshlrev_b32_e32 v6, 2, v6
	v_mov_b32_e32 v7, v75
	v_mul_u32_u24_e32 v8, s24, v90
	v_lshl_add_u64 v[6:7], s[22:23], 0, v[6:7]
	v_lshlrev_b32_e32 v8, 2, v8
	v_mov_b32_e32 v9, v75
	v_lshl_add_u64 v[6:7], v[6:7], 0, v[86:87]
	v_lshl_add_u64 v[8:9], s[22:23], 0, v[8:9]
	v_lshl_add_u64 v[8:9], v[8:9], 0, v[86:87]
	global_load_dwordx4 v[70:73], v[6:7], off nt
	global_load_dwordx4 v[62:65], v[8:9], off nt
	s_waitcnt vmcnt(19)
	ds_write2_b32 v95, v22, v23 offset1:1
	ds_write2_b32 v95, v24, v25 offset0:2 offset1:3
	s_waitcnt vmcnt(18)
	ds_write2_b32 v96, v18, v19 offset1:1
	ds_write2_b32 v97, v20, v21 offset1:1
	s_waitcnt vmcnt(17)
	ds_write2_b32 v98, v38, v39 offset1:1
	ds_write2_b32 v99, v40, v41 offset1:1
	s_waitcnt vmcnt(16)
	ds_write2_b32 v100, v34, v35 offset1:1
	ds_write2_b32 v101, v36, v37 offset1:1
	s_waitcnt vmcnt(15)
	ds_write2_b32 v102, v54, v55 offset1:1
	ds_write2_b32 v103, v56, v57 offset1:1
	s_waitcnt vmcnt(14)
	ds_write2_b32 v104, v50, v51 offset1:1
	ds_write2_b32 v105, v52, v53 offset1:1
	s_waitcnt vmcnt(13)
	ds_write2_b32 v106, v66, v67 offset1:1
	ds_write2_b32 v107, v68, v69 offset1:1
	s_waitcnt vmcnt(12)
	ds_write2_b32 v108, v58, v59 offset1:1
	ds_write2_b32 v109, v60, v61 offset1:1
	s_waitcnt lgkmcnt(0)
	ds_read2_b32 v[14:15], v94 offset1:8
	ds_read2_b32 v[18:19], v94 offset0:33 offset1:41
	ds_read2_b32 v[20:21], v94 offset0:66 offset1:74
	ds_read2_b32 v[22:23], v94 offset0:99 offset1:107
	ds_read2_b32 v[24:25], v94 offset0:132 offset1:140
	s_waitcnt lgkmcnt(4)
	v_bfe_u32 v6, v14, 16, 1
	v_add3_u32 v6, v14, v6, s28
	s_waitcnt lgkmcnt(3)
	v_bfe_u32 v7, v18, 16, 1
	v_lshrrev_b32_e32 v6, 16, v6
	v_add3_u32 v7, v18, v7, s28
	ds_read2_b32 v[34:35], v94 offset0:165 offset1:173
	v_and_or_b32 v6, v7, s29, v6
	s_waitcnt lgkmcnt(3)
	v_bfe_u32 v7, v20, 16, 1
	v_add3_u32 v7, v20, v7, s28
	s_waitcnt lgkmcnt(2)
	v_bfe_u32 v8, v22, 16, 1
	ds_read2_b32 v[36:37], v94 offset0:198 offset1:206
	v_lshrrev_b32_e32 v7, 16, v7
	v_add3_u32 v8, v22, v8, s28
	ds_read2_b32 v[38:39], v94 offset0:231 offset1:239
	s_lshl_b64 s[16:17], s[16:17], 12
	v_and_or_b32 v7, v8, s29, v7
	s_waitcnt lgkmcnt(3)
	v_bfe_u32 v8, v24, 16, 1
	s_add_u32 s20, s20, s16
	v_add3_u32 v8, v24, v8, s28
	s_waitcnt lgkmcnt(2)
	v_bfe_u32 v9, v34, 16, 1
	s_addc_u32 s21, s21, s17
	s_lshl_b64 s[16:17], s[0:1], 1
	v_lshrrev_b32_e32 v8, 16, v8
	v_add3_u32 v9, v34, v9, s28
	s_add_u32 s16, s20, s16
	v_and_or_b32 v8, v9, s29, v8
	s_waitcnt lgkmcnt(1)
	v_bfe_u32 v9, v36, 16, 1
	s_addc_u32 s17, s21, s17
	v_add3_u32 v9, v36, v9, s28
	s_waitcnt lgkmcnt(0)
	v_bfe_u32 v14, v38, 16, 1
	v_lshl_add_u64 v[16:17], s[16:17], 0, v[74:75]
	v_lshrrev_b32_e32 v9, 16, v9
	v_add3_u32 v14, v38, v14, s28
	v_and_or_b32 v9, v14, s29, v9
	v_lshl_add_u64 v[40:41], v[16:17], 0, v[78:79]
	global_store_dwordx4 v[40:41], v[6:9], off
	v_bfe_u32 v14, v39, 16, 1
	v_add3_u32 v18, v39, v14, s28
	v_bfe_u32 v6, v15, 16, 1
	v_add3_u32 v6, v15, v6, s28
	v_bfe_u32 v7, v19, 16, 1
	v_lshrrev_b32_e32 v6, 16, v6
	v_add3_u32 v7, v19, v7, s28
	v_and_or_b32 v6, v7, s29, v6
	v_bfe_u32 v7, v21, 16, 1
	v_add3_u32 v7, v21, v7, s28
	v_bfe_u32 v8, v23, 16, 1
	v_lshrrev_b32_e32 v7, 16, v7
	v_add3_u32 v8, v23, v8, s28
	v_and_or_b32 v7, v8, s29, v7
	v_bfe_u32 v8, v25, 16, 1
	v_add3_u32 v8, v25, v8, s28
	v_bfe_u32 v9, v35, 16, 1
	v_lshrrev_b32_e32 v8, 16, v8
	v_add3_u32 v9, v35, v9, s28
	v_and_or_b32 v8, v9, s29, v8
	v_bfe_u32 v9, v37, 16, 1
	v_add3_u32 v9, v37, v9, s28
	v_lshrrev_b32_e32 v9, 16, v9
	ds_read2_b32 v[14:15], v94 offset0:16 offset1:24
	v_and_or_b32 v9, v18, s29, v9
	v_lshl_add_u64 v[18:19], v[16:17], 0, v[80:81]
	global_store_dwordx4 v[18:19], v[6:9], off
	ds_read2_b32 v[18:19], v94 offset0:49 offset1:57
	ds_read2_b32 v[20:21], v94 offset0:82 offset1:90
	ds_read2_b32 v[22:23], v94 offset0:115 offset1:123
	s_waitcnt lgkmcnt(3)
	v_bfe_u32 v6, v14, 16, 1
	v_add3_u32 v6, v14, v6, s28
	s_waitcnt lgkmcnt(2)
	v_bfe_u32 v7, v18, 16, 1
	ds_read2_b32 v[24:25], v94 offset0:148 offset1:156
	v_lshrrev_b32_e32 v6, 16, v6
	v_add3_u32 v7, v18, v7, s28
	ds_read2_b32 v[34:35], v94 offset0:181 offset1:189
	v_and_or_b32 v6, v7, s29, v6
	s_waitcnt lgkmcnt(3)
	v_bfe_u32 v7, v20, 16, 1
	v_add3_u32 v7, v20, v7, s28
	s_waitcnt lgkmcnt(2)
	v_bfe_u32 v8, v22, 16, 1
	ds_read2_b32 v[36:37], v94 offset0:214 offset1:222
	v_lshrrev_b32_e32 v7, 16, v7
	v_add3_u32 v8, v22, v8, s28
	ds_read2_b32 v[38:39], v94 offset0:247 offset1:255
	v_and_or_b32 v7, v8, s29, v7
	s_waitcnt lgkmcnt(3)
	v_bfe_u32 v8, v24, 16, 1
	v_add3_u32 v8, v24, v8, s28
	s_waitcnt lgkmcnt(2)
	v_bfe_u32 v9, v34, 16, 1
	v_lshrrev_b32_e32 v8, 16, v8
	v_add3_u32 v9, v34, v9, s28
	v_and_or_b32 v8, v9, s29, v8
	s_waitcnt lgkmcnt(1)
	v_bfe_u32 v9, v36, 16, 1
	v_add3_u32 v9, v36, v9, s28
	s_waitcnt lgkmcnt(0)
	v_bfe_u32 v14, v38, 16, 1
	v_lshrrev_b32_e32 v9, 16, v9
	v_add3_u32 v14, v38, v14, s28
	v_and_or_b32 v9, v14, s29, v9
	v_lshl_add_u64 v[40:41], v[16:17], 0, v[82:83]
	global_store_dwordx4 v[40:41], v[6:9], off
	v_bfe_u32 v14, v39, 16, 1
	v_add3_u32 v14, v39, v14, s28
	v_bfe_u32 v6, v15, 16, 1
	v_add3_u32 v6, v15, v6, s28
	v_bfe_u32 v7, v19, 16, 1
	v_lshrrev_b32_e32 v6, 16, v6
	v_add3_u32 v7, v19, v7, s28
	v_and_or_b32 v6, v7, s29, v6
	v_bfe_u32 v7, v21, 16, 1
	v_add3_u32 v7, v21, v7, s28
	v_bfe_u32 v8, v23, 16, 1
	v_lshrrev_b32_e32 v7, 16, v7
	v_add3_u32 v8, v23, v8, s28
	v_and_or_b32 v7, v8, s29, v7
	v_bfe_u32 v8, v25, 16, 1
	v_add3_u32 v8, v25, v8, s28
	v_bfe_u32 v9, v35, 16, 1
	v_lshrrev_b32_e32 v8, 16, v8
	v_add3_u32 v9, v35, v9, s28
	v_and_or_b32 v8, v9, s29, v8
	v_bfe_u32 v9, v37, 16, 1
	v_add3_u32 v9, v37, v9, s28
	v_lshrrev_b32_e32 v9, 16, v9
	v_and_or_b32 v9, v14, s29, v9
	v_lshl_add_u64 v[14:15], v[16:17], 0, v[84:85]
	global_store_dwordx4 v[14:15], v[6:9], off
	s_waitcnt lgkmcnt(0)
	s_add_i32 s31, s30, 4
	s_cmpk_lt_u32 s30, 0x3fc
	s_mov_b64 s[26:27], -1
	s_cbranch_scc1 .LBB0_579
	s_cmpk_lt_u32 s30, 0x7fc
	s_cbranch_scc1 .LBB0_576
	s_cmpk_lt_u32 s30, 0xffc
	s_mov_b64 s[20:21], -1
	s_cbranch_scc1 .LBB0_573
	s_add_i32 s0, s31, 0xf000
	s_and_b32 s16, s0, 0xffff
	s_mul_i32 s16, s16, 0xba2f
	s_lshr_b32 s17, s16, 24
	s_mul_i32 s16, s17, 0x160
	s_sub_i32 s20, s0, s16
	s_lshl_b32 s0, s20, 5
	s_and_b32 s16, s20, 0xffff
	s_add_i32 s21, s0, 0xea00
	s_cmpk_gt_u32 s16, 0xaf
	s_cselect_b32 s0, s21, s0
	s_sext_i32_i16 s16, s0
	s_cselect_b32 s21, 0x80, 0
	s_bfe_u32 s16, s16, 0x70018
	s_add_i32 s16, s0, s16
	s_sext_i32_i16 s22, s16
	s_and_b32 s16, s16, 0xff80
	s_sub_i32 s0, s0, s16
	s_lshl_b32 s22, s22, 1
	s_sext_i32_i16 s0, s0
	s_and_b32 s22, s22, 0xffffff00
	s_add_i32 s0, s21, s0
	s_add_i32 s16, s0, s22
	s_lshl_b32 s0, s17, 6
	s_mul_i32 s17, s17, 0x2c0000
	s_add_u32 s17, s84, s17
	s_addc_u32 s21, s85, 0
	s_lshl_b32 s20, s20, 7
	s_and_b32 s20, s20, 0x3ff80
	s_add_u32 s22, s17, s20
	s_addc_u32 s23, s21, 0
	s_ashr_i32 s17, s16, 31
	s_mov_b64 s[20:21], 0

.LBB0_581:
	v_mul_u32_u24_e32 v6, s24, v1
	v_mul_u32_u24_e32 v8, s24, v91
	v_mul_u32_u24_e32 v18, s24, v92
	v_mul_u32_u24_e32 v20, s24, v93
	v_mul_u32_u24_e32 v22, s24, v77
	v_lshlrev_b32_e32 v6, 2, v6
	v_mov_b32_e32 v7, v75
	v_lshlrev_b32_e32 v8, 2, v8
	v_mov_b32_e32 v9, v75
	v_lshlrev_b32_e32 v18, 2, v18
	v_mov_b32_e32 v19, v75
	v_lshlrev_b32_e32 v20, 2, v20
	v_mov_b32_e32 v21, v75
	v_lshlrev_b32_e32 v22, 2, v22
	v_mov_b32_e32 v23, v75
	v_mul_u32_u24_e32 v24, s24, v88
	v_lshl_add_u64 v[6:7], s[22:23], 0, v[6:7]
	v_mov_b32_e32 v87, v75
	v_lshl_add_u64 v[8:9], s[22:23], 0, v[8:9]
	v_lshl_add_u64 v[18:19], s[22:23], 0, v[18:19]
	v_lshl_add_u64 v[20:21], s[22:23], 0, v[20:21]
	v_lshl_add_u64 v[22:23], s[22:23], 0, v[22:23]
	v_lshlrev_b32_e32 v24, 2, v24
	v_mov_b32_e32 v25, v75
	v_lshl_add_u64 v[6:7], v[6:7], 0, v[86:87]
	v_lshl_add_u64 v[8:9], v[8:9], 0, v[86:87]
	v_lshl_add_u64 v[18:19], v[18:19], 0, v[86:87]
	v_lshl_add_u64 v[20:21], v[20:21], 0, v[86:87]
	v_lshl_add_u64 v[22:23], v[22:23], 0, v[86:87]
	v_lshl_add_u64 v[24:25], s[22:23], 0, v[24:25]
	global_load_dwordx4 v[14:17], v[6:7], off nt
	s_nop 0
	global_load_dwordx4 v[6:9], v[8:9], off nt
	s_nop 0
	global_load_dwordx4 v[34:37], v[18:19], off nt
	s_nop 0
	global_load_dwordx4 v[18:21], v[20:21], off nt
	v_lshl_add_u64 v[24:25], v[24:25], 0, v[86:87]
	global_load_dwordx4 v[50:53], v[22:23], off nt
	global_load_dwordx4 v[38:41], v[24:25], off nt
	v_mul_u32_u24_e32 v22, s24, v89
	v_lshlrev_b32_e32 v22, 2, v22
	v_mov_b32_e32 v23, v75
	v_mul_u32_u24_e32 v24, s24, v90
	v_lshl_add_u64 v[22:23], s[22:23], 0, v[22:23]
	v_lshlrev_b32_e32 v24, 2, v24
	v_mov_b32_e32 v25, v75
	v_lshl_add_u64 v[22:23], v[22:23], 0, v[86:87]
	v_lshl_add_u64 v[24:25], s[22:23], 0, v[24:25]
	v_lshl_add_u64 v[24:25], v[24:25], 0, v[86:87]
	global_load_dwordx4 v[66:69], v[22:23], off nt
	global_load_dwordx4 v[54:57], v[24:25], off nt
	s_waitcnt vmcnt(19)
	ds_write2_b32 v95, v10, v11 offset1:1
	ds_write2_b32 v95, v12, v13 offset0:2 offset1:3
	s_waitcnt vmcnt(18)
	ds_write2_b32 v96, v2, v3 offset1:1
	ds_write2_b32 v97, v4, v5 offset1:1
	s_waitcnt vmcnt(17)
	ds_write2_b32 v98, v30, v31 offset1:1
	ds_write2_b32 v99, v32, v33 offset1:1
	s_waitcnt vmcnt(16)
	ds_write2_b32 v100, v26, v27 offset1:1
	ds_write2_b32 v101, v28, v29 offset1:1
	s_waitcnt vmcnt(15)
	ds_write2_b32 v102, v46, v47 offset1:1
	ds_write2_b32 v103, v48, v49 offset1:1
	s_waitcnt vmcnt(14)
	ds_write2_b32 v104, v42, v43 offset1:1
	ds_write2_b32 v105, v44, v45 offset1:1
	s_waitcnt vmcnt(13)
	ds_write2_b32 v106, v70, v71 offset1:1
	ds_write2_b32 v107, v72, v73 offset1:1
	s_waitcnt vmcnt(12)
	ds_write2_b32 v108, v62, v63 offset1:1
	ds_write2_b32 v109, v64, v65 offset1:1
	s_waitcnt lgkmcnt(0)
	ds_read2_b32 v[10:11], v94 offset1:8
	ds_read2_b32 v[22:23], v94 offset0:33 offset1:41
	ds_read2_b32 v[24:25], v94 offset0:66 offset1:74
	ds_read2_b32 v[26:27], v94 offset0:99 offset1:107
	ds_read2_b32 v[28:29], v94 offset0:132 offset1:140
	s_waitcnt lgkmcnt(4)
	v_bfe_u32 v2, v10, 16, 1
	v_add3_u32 v2, v10, v2, s28
	s_waitcnt lgkmcnt(3)
	v_bfe_u32 v3, v22, 16, 1
	v_lshrrev_b32_e32 v2, 16, v2
	v_add3_u32 v3, v22, v3, s28
	ds_read2_b32 v[30:31], v94 offset0:165 offset1:173
	v_and_or_b32 v2, v3, s29, v2
	s_waitcnt lgkmcnt(3)
	v_bfe_u32 v3, v24, 16, 1
	v_add3_u32 v3, v24, v3, s28
	s_waitcnt lgkmcnt(2)
	v_bfe_u32 v4, v26, 16, 1
	ds_read2_b32 v[32:33], v94 offset0:198 offset1:206
	v_lshrrev_b32_e32 v3, 16, v3
	v_add3_u32 v4, v26, v4, s28
	ds_read2_b32 v[42:43], v94 offset0:231 offset1:239
	s_lshl_b64 s[14:15], s[14:15], 12
	v_and_or_b32 v3, v4, s29, v3
	s_waitcnt lgkmcnt(3)
	v_bfe_u32 v4, v28, 16, 1
	s_add_u32 s14, s18, s14
	v_add3_u32 v4, v28, v4, s28
	s_waitcnt lgkmcnt(2)
	v_bfe_u32 v5, v30, 16, 1
	s_addc_u32 s15, s19, s15
	s_lshl_b64 s[6:7], s[6:7], 1
	v_lshrrev_b32_e32 v4, 16, v4
	v_add3_u32 v5, v30, v5, s28
	s_add_u32 s6, s14, s6
	v_and_or_b32 v4, v5, s29, v4
	s_waitcnt lgkmcnt(1)
	v_bfe_u32 v5, v32, 16, 1
	s_addc_u32 s7, s15, s7
	v_add3_u32 v5, v32, v5, s28
	s_waitcnt lgkmcnt(0)
	v_bfe_u32 v10, v42, 16, 1
	v_lshl_add_u64 v[12:13], s[6:7], 0, v[74:75]
	v_lshrrev_b32_e32 v5, 16, v5
	v_add3_u32 v10, v42, v10, s28
	v_and_or_b32 v5, v10, s29, v5
	v_lshl_add_u64 v[44:45], v[12:13], 0, v[78:79]
	global_store_dwordx4 v[44:45], v[2:5], off
	v_bfe_u32 v10, v43, 16, 1
	v_add3_u32 v22, v43, v10, s28
	v_bfe_u32 v2, v11, 16, 1
	v_add3_u32 v2, v11, v2, s28
	v_bfe_u32 v3, v23, 16, 1
	v_lshrrev_b32_e32 v2, 16, v2
	v_add3_u32 v3, v23, v3, s28
	v_and_or_b32 v2, v3, s29, v2
	v_bfe_u32 v3, v25, 16, 1
	v_add3_u32 v3, v25, v3, s28
	v_bfe_u32 v4, v27, 16, 1
	v_lshrrev_b32_e32 v3, 16, v3
	v_add3_u32 v4, v27, v4, s28
	v_and_or_b32 v3, v4, s29, v3
	v_bfe_u32 v4, v29, 16, 1
	v_add3_u32 v4, v29, v4, s28
	v_bfe_u32 v5, v31, 16, 1
	v_lshrrev_b32_e32 v4, 16, v4
	v_add3_u32 v5, v31, v5, s28
	v_and_or_b32 v4, v5, s29, v4
	v_bfe_u32 v5, v33, 16, 1
	v_add3_u32 v5, v33, v5, s28
	v_lshrrev_b32_e32 v5, 16, v5
	ds_read2_b32 v[10:11], v94 offset0:16 offset1:24
	v_and_or_b32 v5, v22, s29, v5
	v_lshl_add_u64 v[22:23], v[12:13], 0, v[80:81]
	global_store_dwordx4 v[22:23], v[2:5], off
	ds_read2_b32 v[22:23], v94 offset0:49 offset1:57
	ds_read2_b32 v[24:25], v94 offset0:82 offset1:90
	ds_read2_b32 v[26:27], v94 offset0:115 offset1:123
	s_waitcnt lgkmcnt(3)
	v_bfe_u32 v2, v10, 16, 1
	v_add3_u32 v2, v10, v2, s28
	s_waitcnt lgkmcnt(2)
	v_bfe_u32 v3, v22, 16, 1
	ds_read2_b32 v[28:29], v94 offset0:148 offset1:156
	v_lshrrev_b32_e32 v2, 16, v2
	v_add3_u32 v3, v22, v3, s28
	ds_read2_b32 v[30:31], v94 offset0:181 offset1:189
	v_and_or_b32 v2, v3, s29, v2
	s_waitcnt lgkmcnt(3)
	v_bfe_u32 v3, v24, 16, 1
	v_add3_u32 v3, v24, v3, s28
	s_waitcnt lgkmcnt(2)
	v_bfe_u32 v4, v26, 16, 1
	ds_read2_b32 v[32:33], v94 offset0:214 offset1:222
	v_lshrrev_b32_e32 v3, 16, v3
	v_add3_u32 v4, v26, v4, s28
	ds_read2_b32 v[42:43], v94 offset0:247 offset1:255
	v_and_or_b32 v3, v4, s29, v3
	s_waitcnt lgkmcnt(3)
	v_bfe_u32 v4, v28, 16, 1
	v_add3_u32 v4, v28, v4, s28
	s_waitcnt lgkmcnt(2)
	v_bfe_u32 v5, v30, 16, 1
	v_lshrrev_b32_e32 v4, 16, v4
	v_add3_u32 v5, v30, v5, s28
	v_and_or_b32 v4, v5, s29, v4
	s_waitcnt lgkmcnt(1)
	v_bfe_u32 v5, v32, 16, 1
	v_add3_u32 v5, v32, v5, s28
	s_waitcnt lgkmcnt(0)
	v_bfe_u32 v10, v42, 16, 1
	v_lshrrev_b32_e32 v5, 16, v5
	v_add3_u32 v10, v42, v10, s28
	v_and_or_b32 v5, v10, s29, v5
	v_lshl_add_u64 v[44:45], v[12:13], 0, v[82:83]
	global_store_dwordx4 v[44:45], v[2:5], off
	v_bfe_u32 v10, v43, 16, 1
	v_add3_u32 v10, v43, v10, s28
	v_bfe_u32 v2, v11, 16, 1
	v_add3_u32 v2, v11, v2, s28
	v_bfe_u32 v3, v23, 16, 1
	v_lshrrev_b32_e32 v2, 16, v2
	v_add3_u32 v3, v23, v3, s28
	v_and_or_b32 v2, v3, s29, v2
	v_bfe_u32 v3, v25, 16, 1
	v_add3_u32 v3, v25, v3, s28
	v_bfe_u32 v4, v27, 16, 1
	v_lshrrev_b32_e32 v3, 16, v3
	v_add3_u32 v4, v27, v4, s28
	v_and_or_b32 v3, v4, s29, v3
	v_bfe_u32 v4, v29, 16, 1
	v_add3_u32 v4, v29, v4, s28
	v_bfe_u32 v5, v31, 16, 1
	v_lshrrev_b32_e32 v4, 16, v4
	v_add3_u32 v5, v31, v5, s28
	v_and_or_b32 v4, v5, s29, v4
	v_bfe_u32 v5, v33, 16, 1
	v_add3_u32 v5, v33, v5, s28
	v_lshrrev_b32_e32 v5, 16, v5
	v_and_or_b32 v5, v10, s29, v5
	v_lshl_add_u64 v[10:11], v[12:13], 0, v[84:85]
	global_store_dwordx4 v[10:11], v[2:5], off
	s_waitcnt lgkmcnt(0)
	s_add_i32 s31, s30, 5
	s_cmpk_lt_u32 s30, 0x3fb
	s_mov_b64 s[26:27], -1
	s_cbranch_scc1 .LBB0_591
	s_cmpk_lt_u32 s30, 0x7fb
	s_cbranch_scc1 .LBB0_588
	s_cmpk_lt_u32 s30, 0xffb
	s_mov_b64 s[18:19], -1
	s_cbranch_scc1 .LBB0_585
	s_add_i32 s6, s31, 0xf000
	s_and_b32 s7, s6, 0xffff
	s_mul_i32 s7, s7, 0xba2f
	s_lshr_b32 s15, s7, 24
	s_mul_i32 s7, s15, 0x160
	s_sub_i32 s18, s6, s7
	s_lshl_b32 s6, s18, 5
	s_and_b32 s7, s18, 0xffff
	s_add_i32 s14, s6, 0xea00
	s_cmpk_gt_u32 s7, 0xaf
	s_cselect_b32 s6, s14, s6
	s_sext_i32_i16 s7, s6
	s_cselect_b32 s14, 0x80, 0
	s_bfe_u32 s7, s7, 0x70018
	s_add_i32 s7, s6, s7
	s_sext_i32_i16 s19, s7
	s_and_b32 s7, s7, 0xff80
	s_sub_i32 s6, s6, s7
	s_lshl_b32 s19, s19, 1
	s_sext_i32_i16 s6, s6
	s_and_b32 s19, s19, 0xffffff00
	s_add_i32 s6, s14, s6
	s_add_i32 s14, s6, s19
	s_lshl_b32 s6, s15, 6
	s_mul_i32 s15, s15, 0x2c0000
	s_add_u32 s15, s84, s15
	s_addc_u32 s19, s85, 0
	s_lshl_b32 s18, s18, 7
	s_and_b32 s18, s18, 0x3ff80
	s_add_u32 s22, s15, s18
	s_mov_b32 s7, s1
	s_addc_u32 s23, s19, 0
	s_ashr_i32 s15, s14, 31
	s_mov_b64 s[18:19], 0

.LBB0_593:
	v_mul_u32_u24_e32 v2, s24, v1
	v_mul_u32_u24_e32 v4, s24, v91
	v_mul_u32_u24_e32 v22, s24, v92
	v_mul_u32_u24_e32 v24, s24, v93
	v_mul_u32_u24_e32 v30, s24, v77
	v_lshlrev_b32_e32 v2, 2, v2
	v_mov_b32_e32 v3, v75
	v_lshlrev_b32_e32 v4, 2, v4
	v_mov_b32_e32 v5, v75
	v_lshlrev_b32_e32 v22, 2, v22
	v_mov_b32_e32 v23, v75
	v_lshlrev_b32_e32 v24, 2, v24
	v_mov_b32_e32 v25, v75
	v_lshlrev_b32_e32 v30, 2, v30
	v_mov_b32_e32 v31, v75
	v_mul_u32_u24_e32 v32, s24, v88
	v_lshl_add_u64 v[2:3], s[22:23], 0, v[2:3]
	v_mov_b32_e32 v87, v75
	v_lshl_add_u64 v[4:5], s[22:23], 0, v[4:5]
	v_lshl_add_u64 v[22:23], s[22:23], 0, v[22:23]
	v_lshl_add_u64 v[24:25], s[22:23], 0, v[24:25]
	v_lshl_add_u64 v[30:31], s[22:23], 0, v[30:31]
	v_lshlrev_b32_e32 v32, 2, v32
	v_mov_b32_e32 v33, v75
	v_lshl_add_u64 v[2:3], v[2:3], 0, v[86:87]
	v_lshl_add_u64 v[4:5], v[4:5], 0, v[86:87]
	v_lshl_add_u64 v[22:23], v[22:23], 0, v[86:87]
	v_lshl_add_u64 v[24:25], v[24:25], 0, v[86:87]
	v_lshl_add_u64 v[30:31], v[30:31], 0, v[86:87]
	v_lshl_add_u64 v[32:33], s[22:23], 0, v[32:33]
	global_load_dwordx4 v[10:13], v[2:3], off nt
	s_nop 0
	global_load_dwordx4 v[2:5], v[4:5], off nt
	s_nop 0
	global_load_dwordx4 v[26:29], v[22:23], off nt
	s_nop 0
	global_load_dwordx4 v[22:25], v[24:25], off nt
	v_lshl_add_u64 v[32:33], v[32:33], 0, v[86:87]
	global_load_dwordx4 v[46:49], v[30:31], off nt
	global_load_dwordx4 v[42:45], v[32:33], off nt
	v_mul_u32_u24_e32 v30, s24, v89
	v_lshlrev_b32_e32 v30, 2, v30
	v_mov_b32_e32 v31, v75
	v_mul_u32_u24_e32 v32, s24, v90
	v_lshl_add_u64 v[30:31], s[22:23], 0, v[30:31]
	v_lshlrev_b32_e32 v32, 2, v32
	v_mov_b32_e32 v33, v75
	v_lshl_add_u64 v[30:31], v[30:31], 0, v[86:87]
	v_lshl_add_u64 v[32:33], s[22:23], 0, v[32:33]
	v_lshl_add_u64 v[32:33], v[32:33], 0, v[86:87]
	global_load_dwordx4 v[62:65], v[30:31], off nt
	global_load_dwordx4 v[58:61], v[32:33], off nt
	s_waitcnt vmcnt(19)
	ds_write2_b32 v95, v14, v15 offset1:1
	ds_write2_b32 v95, v16, v17 offset0:2 offset1:3
	s_waitcnt vmcnt(18)
	ds_write2_b32 v96, v6, v7 offset1:1
	ds_write2_b32 v97, v8, v9 offset1:1
	s_waitcnt vmcnt(17)
	ds_write2_b32 v98, v34, v35 offset1:1
	ds_write2_b32 v99, v36, v37 offset1:1
	s_waitcnt vmcnt(16)
	ds_write2_b32 v100, v18, v19 offset1:1
	ds_write2_b32 v101, v20, v21 offset1:1
	s_waitcnt vmcnt(15)
	ds_write2_b32 v102, v50, v51 offset1:1
	ds_write2_b32 v103, v52, v53 offset1:1
	s_waitcnt vmcnt(14)
	ds_write2_b32 v104, v38, v39 offset1:1
	ds_write2_b32 v105, v40, v41 offset1:1
	s_waitcnt vmcnt(13)
	ds_write2_b32 v106, v66, v67 offset1:1
	ds_write2_b32 v107, v68, v69 offset1:1
	s_waitcnt vmcnt(12)
	ds_write2_b32 v108, v54, v55 offset1:1
	ds_write2_b32 v109, v56, v57 offset1:1
	s_waitcnt lgkmcnt(0)
	ds_read2_b32 v[14:15], v94 offset1:8
	ds_read2_b32 v[18:19], v94 offset0:33 offset1:41
	ds_read2_b32 v[20:21], v94 offset0:66 offset1:74
	ds_read2_b32 v[30:31], v94 offset0:99 offset1:107
	ds_read2_b32 v[32:33], v94 offset0:132 offset1:140
	s_waitcnt lgkmcnt(4)
	v_bfe_u32 v6, v14, 16, 1
	v_add3_u32 v6, v14, v6, s28
	s_waitcnt lgkmcnt(3)
	v_bfe_u32 v7, v18, 16, 1
	v_lshrrev_b32_e32 v6, 16, v6
	v_add3_u32 v7, v18, v7, s28
	ds_read2_b32 v[34:35], v94 offset0:165 offset1:173
	v_and_or_b32 v6, v7, s29, v6
	s_waitcnt lgkmcnt(3)
	v_bfe_u32 v7, v20, 16, 1
	v_add3_u32 v7, v20, v7, s28
	s_waitcnt lgkmcnt(2)
	v_bfe_u32 v8, v30, 16, 1
	ds_read2_b32 v[36:37], v94 offset0:198 offset1:206
	v_lshrrev_b32_e32 v7, 16, v7
	v_add3_u32 v8, v30, v8, s28
	ds_read2_b32 v[38:39], v94 offset0:231 offset1:239
	s_lshl_b64 s[16:17], s[16:17], 12
	v_and_or_b32 v7, v8, s29, v7
	s_waitcnt lgkmcnt(3)
	v_bfe_u32 v8, v32, 16, 1
	s_add_u32 s20, s20, s16
	v_add3_u32 v8, v32, v8, s28
	s_waitcnt lgkmcnt(2)
	v_bfe_u32 v9, v34, 16, 1
	s_addc_u32 s21, s21, s17
	s_lshl_b64 s[16:17], s[0:1], 1
	v_lshrrev_b32_e32 v8, 16, v8
	v_add3_u32 v9, v34, v9, s28
	s_add_u32 s16, s20, s16
	v_and_or_b32 v8, v9, s29, v8
	s_waitcnt lgkmcnt(1)
	v_bfe_u32 v9, v36, 16, 1
	s_addc_u32 s17, s21, s17
	v_add3_u32 v9, v36, v9, s28
	s_waitcnt lgkmcnt(0)
	v_bfe_u32 v14, v38, 16, 1
	v_lshl_add_u64 v[16:17], s[16:17], 0, v[74:75]
	v_lshrrev_b32_e32 v9, 16, v9
	v_add3_u32 v14, v38, v14, s28
	v_and_or_b32 v9, v14, s29, v9
	v_lshl_add_u64 v[40:41], v[16:17], 0, v[78:79]
	global_store_dwordx4 v[40:41], v[6:9], off
	v_bfe_u32 v14, v39, 16, 1
	v_add3_u32 v18, v39, v14, s28
	v_bfe_u32 v6, v15, 16, 1
	v_add3_u32 v6, v15, v6, s28
	v_bfe_u32 v7, v19, 16, 1
	v_lshrrev_b32_e32 v6, 16, v6
	v_add3_u32 v7, v19, v7, s28
	v_and_or_b32 v6, v7, s29, v6
	v_bfe_u32 v7, v21, 16, 1
	v_add3_u32 v7, v21, v7, s28
	v_bfe_u32 v8, v31, 16, 1
	v_lshrrev_b32_e32 v7, 16, v7
	v_add3_u32 v8, v31, v8, s28
	v_and_or_b32 v7, v8, s29, v7
	v_bfe_u32 v8, v33, 16, 1
	v_add3_u32 v8, v33, v8, s28
	v_bfe_u32 v9, v35, 16, 1
	v_lshrrev_b32_e32 v8, 16, v8
	v_add3_u32 v9, v35, v9, s28
	v_and_or_b32 v8, v9, s29, v8
	v_bfe_u32 v9, v37, 16, 1
	v_add3_u32 v9, v37, v9, s28
	v_lshrrev_b32_e32 v9, 16, v9
	ds_read2_b32 v[14:15], v94 offset0:16 offset1:24
	v_and_or_b32 v9, v18, s29, v9
	v_lshl_add_u64 v[18:19], v[16:17], 0, v[80:81]
	global_store_dwordx4 v[18:19], v[6:9], off
	ds_read2_b32 v[18:19], v94 offset0:49 offset1:57
	ds_read2_b32 v[20:21], v94 offset0:82 offset1:90
	ds_read2_b32 v[30:31], v94 offset0:115 offset1:123
	s_waitcnt lgkmcnt(3)
	v_bfe_u32 v6, v14, 16, 1
	v_add3_u32 v6, v14, v6, s28
	s_waitcnt lgkmcnt(2)
	v_bfe_u32 v7, v18, 16, 1
	ds_read2_b32 v[32:33], v94 offset0:148 offset1:156
	v_lshrrev_b32_e32 v6, 16, v6
	v_add3_u32 v7, v18, v7, s28
	ds_read2_b32 v[34:35], v94 offset0:181 offset1:189
	v_and_or_b32 v6, v7, s29, v6
	s_waitcnt lgkmcnt(3)
	v_bfe_u32 v7, v20, 16, 1
	v_add3_u32 v7, v20, v7, s28
	s_waitcnt lgkmcnt(2)
	v_bfe_u32 v8, v30, 16, 1
	ds_read2_b32 v[36:37], v94 offset0:214 offset1:222
	v_lshrrev_b32_e32 v7, 16, v7
	v_add3_u32 v8, v30, v8, s28
	ds_read2_b32 v[38:39], v94 offset0:247 offset1:255
	v_and_or_b32 v7, v8, s29, v7
	s_waitcnt lgkmcnt(3)
	v_bfe_u32 v8, v32, 16, 1
	v_add3_u32 v8, v32, v8, s28
	s_waitcnt lgkmcnt(2)
	v_bfe_u32 v9, v34, 16, 1
	v_lshrrev_b32_e32 v8, 16, v8
	v_add3_u32 v9, v34, v9, s28
	v_and_or_b32 v8, v9, s29, v8
	s_waitcnt lgkmcnt(1)
	v_bfe_u32 v9, v36, 16, 1
	v_add3_u32 v9, v36, v9, s28
	s_waitcnt lgkmcnt(0)
	v_bfe_u32 v14, v38, 16, 1
	v_lshrrev_b32_e32 v9, 16, v9
	v_add3_u32 v14, v38, v14, s28
	v_and_or_b32 v9, v14, s29, v9
	v_lshl_add_u64 v[40:41], v[16:17], 0, v[82:83]
	global_store_dwordx4 v[40:41], v[6:9], off
	v_bfe_u32 v14, v39, 16, 1
	v_add3_u32 v14, v39, v14, s28
	v_bfe_u32 v6, v15, 16, 1
	v_add3_u32 v6, v15, v6, s28
	v_bfe_u32 v7, v19, 16, 1
	v_lshrrev_b32_e32 v6, 16, v6
	v_add3_u32 v7, v19, v7, s28
	v_and_or_b32 v6, v7, s29, v6
	v_bfe_u32 v7, v21, 16, 1
	v_add3_u32 v7, v21, v7, s28
	v_bfe_u32 v8, v31, 16, 1
	v_lshrrev_b32_e32 v7, 16, v7
	v_add3_u32 v8, v31, v8, s28
	v_and_or_b32 v7, v8, s29, v7
	v_bfe_u32 v8, v33, 16, 1
	v_add3_u32 v8, v33, v8, s28
	v_bfe_u32 v9, v35, 16, 1
	v_lshrrev_b32_e32 v8, 16, v8
	v_add3_u32 v9, v35, v9, s28
	v_and_or_b32 v8, v9, s29, v8
	v_bfe_u32 v9, v37, 16, 1
	v_add3_u32 v9, v37, v9, s28
	v_lshrrev_b32_e32 v9, 16, v9
	v_and_or_b32 v9, v14, s29, v9
	v_lshl_add_u64 v[14:15], v[16:17], 0, v[84:85]
	global_store_dwordx4 v[14:15], v[6:9], off
	s_waitcnt lgkmcnt(0)
	s_add_i32 s31, s30, 6
	s_cmpk_lt_u32 s30, 0x3fa
	s_mov_b64 s[26:27], -1
	s_cbranch_scc1 .LBB0_603
	s_cmpk_lt_u32 s30, 0x7fa
	s_cbranch_scc1 .LBB0_600
	s_cmpk_lt_u32 s30, 0xffa
	s_mov_b64 s[20:21], -1
	s_cbranch_scc1 .LBB0_597
	s_add_i32 s0, s31, 0xf000
	s_and_b32 s16, s0, 0xffff
	s_mul_i32 s16, s16, 0xba2f
	s_lshr_b32 s17, s16, 24
	s_mul_i32 s16, s17, 0x160
	s_sub_i32 s20, s0, s16
	s_lshl_b32 s0, s20, 5
	s_and_b32 s16, s20, 0xffff
	s_add_i32 s21, s0, 0xea00
	s_cmpk_gt_u32 s16, 0xaf
	s_cselect_b32 s0, s21, s0
	s_sext_i32_i16 s16, s0
	s_cselect_b32 s21, 0x80, 0
	s_bfe_u32 s16, s16, 0x70018
	s_add_i32 s16, s0, s16
	s_sext_i32_i16 s22, s16
	s_and_b32 s16, s16, 0xff80
	s_sub_i32 s0, s0, s16
	s_lshl_b32 s22, s22, 1
	s_sext_i32_i16 s0, s0
	s_and_b32 s22, s22, 0xffffff00
	s_add_i32 s0, s21, s0
	s_add_i32 s16, s0, s22
	s_lshl_b32 s0, s17, 6
	s_mul_i32 s17, s17, 0x2c0000
	s_add_u32 s17, s84, s17
	s_addc_u32 s21, s85, 0
	s_lshl_b32 s20, s20, 7
	s_and_b32 s20, s20, 0x3ff80
	s_add_u32 s22, s17, s20
	s_addc_u32 s23, s21, 0
	s_ashr_i32 s17, s16, 31
	s_mov_b64 s[20:21], 0

.LBB0_605:
	v_mul_u32_u24_e32 v6, s24, v1
	v_mul_u32_u24_e32 v8, s24, v91
	v_mul_u32_u24_e32 v18, s24, v92
	v_mul_u32_u24_e32 v20, s24, v93
	v_mul_u32_u24_e32 v34, s24, v77
	v_mul_u32_u24_e32 v36, s24, v88
	v_mul_u32_u24_e32 v50, s24, v89
	v_mul_u32_u24_e32 v52, s24, v90
	v_lshlrev_b32_e32 v6, 2, v6
	v_mov_b32_e32 v7, v75
	v_lshlrev_b32_e32 v8, 2, v8
	v_mov_b32_e32 v9, v75
	v_lshlrev_b32_e32 v18, 2, v18
	v_mov_b32_e32 v19, v75
	v_lshlrev_b32_e32 v20, 2, v20
	v_mov_b32_e32 v21, v75
	v_lshlrev_b32_e32 v34, 2, v34
	v_mov_b32_e32 v35, v75
	v_lshlrev_b32_e32 v36, 2, v36
	v_mov_b32_e32 v37, v75
	v_lshlrev_b32_e32 v50, 2, v50
	v_mov_b32_e32 v51, v75
	v_lshlrev_b32_e32 v52, 2, v52
	v_mov_b32_e32 v53, v75
	v_lshl_add_u64 v[6:7], s[22:23], 0, v[6:7]
	v_mov_b32_e32 v87, v75
	v_lshl_add_u64 v[8:9], s[22:23], 0, v[8:9]
	v_lshl_add_u64 v[18:19], s[22:23], 0, v[18:19]
	v_lshl_add_u64 v[20:21], s[22:23], 0, v[20:21]
	v_lshl_add_u64 v[34:35], s[22:23], 0, v[34:35]
	v_lshl_add_u64 v[36:37], s[22:23], 0, v[36:37]
	v_lshl_add_u64 v[50:51], s[22:23], 0, v[50:51]
	v_lshl_add_u64 v[52:53], s[22:23], 0, v[52:53]
	v_lshl_add_u64 v[6:7], v[6:7], 0, v[86:87]
	v_lshl_add_u64 v[8:9], v[8:9], 0, v[86:87]
	v_lshl_add_u64 v[18:19], v[18:19], 0, v[86:87]
	v_lshl_add_u64 v[20:21], v[20:21], 0, v[86:87]
	v_lshl_add_u64 v[34:35], v[34:35], 0, v[86:87]
	v_lshl_add_u64 v[36:37], v[36:37], 0, v[86:87]
	v_lshl_add_u64 v[50:51], v[50:51], 0, v[86:87]
	v_lshl_add_u64 v[52:53], v[52:53], 0, v[86:87]
	global_load_dwordx4 v[14:17], v[6:7], off nt
	s_nop 0
	global_load_dwordx4 v[6:9], v[8:9], off nt
	s_nop 0
	global_load_dwordx4 v[30:33], v[18:19], off nt
	s_nop 0
	global_load_dwordx4 v[18:21], v[20:21], off nt
	s_nop 0
	global_load_dwordx4 v[38:41], v[34:35], off nt
	s_nop 0
	global_load_dwordx4 v[34:37], v[36:37], off nt
	s_nop 0
	global_load_dwordx4 v[54:57], v[50:51], off nt
	s_nop 0
	global_load_dwordx4 v[50:53], v[52:53], off nt
	s_waitcnt vmcnt(19)
	ds_write2_b32 v95, v10, v11 offset1:1
	ds_write2_b32 v95, v12, v13 offset0:2 offset1:3
	s_waitcnt vmcnt(18)
	ds_write2_b32 v96, v2, v3 offset1:1
	ds_write2_b32 v97, v4, v5 offset1:1
	s_waitcnt vmcnt(17)
	ds_write2_b32 v98, v26, v27 offset1:1
	ds_write2_b32 v99, v28, v29 offset1:1
	s_waitcnt vmcnt(16)
	ds_write2_b32 v100, v22, v23 offset1:1
	ds_write2_b32 v101, v24, v25 offset1:1
	s_waitcnt vmcnt(15)
	ds_write2_b32 v102, v46, v47 offset1:1
	ds_write2_b32 v103, v48, v49 offset1:1
	s_waitcnt vmcnt(14)
	ds_write2_b32 v104, v42, v43 offset1:1
	ds_write2_b32 v105, v44, v45 offset1:1
	s_waitcnt vmcnt(13)
	ds_write2_b32 v106, v62, v63 offset1:1
	ds_write2_b32 v107, v64, v65 offset1:1
	s_waitcnt vmcnt(12)
	ds_write2_b32 v108, v58, v59 offset1:1
	ds_write2_b32 v109, v60, v61 offset1:1
	s_waitcnt lgkmcnt(0)
	ds_read2_b32 v[10:11], v94 offset1:8
	ds_read2_b32 v[22:23], v94 offset0:33 offset1:41
	ds_read2_b32 v[24:25], v94 offset0:66 offset1:74
	ds_read2_b32 v[26:27], v94 offset0:99 offset1:107
	ds_read2_b32 v[28:29], v94 offset0:132 offset1:140
	s_waitcnt lgkmcnt(4)
	v_bfe_u32 v2, v10, 16, 1
	v_add3_u32 v2, v10, v2, s28
	s_waitcnt lgkmcnt(3)
	v_bfe_u32 v3, v22, 16, 1
	v_lshrrev_b32_e32 v2, 16, v2
	v_add3_u32 v3, v22, v3, s28
	ds_read2_b32 v[42:43], v94 offset0:165 offset1:173
	v_and_or_b32 v2, v3, s29, v2
	s_waitcnt lgkmcnt(3)
	v_bfe_u32 v3, v24, 16, 1
	v_add3_u32 v3, v24, v3, s28
	s_waitcnt lgkmcnt(2)
	v_bfe_u32 v4, v26, 16, 1
	ds_read2_b32 v[44:45], v94 offset0:198 offset1:206
	v_lshrrev_b32_e32 v3, 16, v3
	v_add3_u32 v4, v26, v4, s28
	ds_read2_b32 v[46:47], v94 offset0:231 offset1:239
	s_lshl_b64 s[14:15], s[14:15], 12
	v_and_or_b32 v3, v4, s29, v3
	s_waitcnt lgkmcnt(3)
	v_bfe_u32 v4, v28, 16, 1
	s_add_u32 s14, s18, s14
	v_add3_u32 v4, v28, v4, s28
	s_waitcnt lgkmcnt(2)
	v_bfe_u32 v5, v42, 16, 1
	s_addc_u32 s15, s19, s15
	s_lshl_b64 s[6:7], s[6:7], 1
	v_lshrrev_b32_e32 v4, 16, v4
	v_add3_u32 v5, v42, v5, s28
	s_add_u32 s6, s14, s6
	v_and_or_b32 v4, v5, s29, v4
	s_waitcnt lgkmcnt(1)
	v_bfe_u32 v5, v44, 16, 1
	s_addc_u32 s7, s15, s7
	v_add3_u32 v5, v44, v5, s28
	s_waitcnt lgkmcnt(0)
	v_bfe_u32 v10, v46, 16, 1
	v_lshl_add_u64 v[12:13], s[6:7], 0, v[74:75]
	v_lshrrev_b32_e32 v5, 16, v5
	v_add3_u32 v10, v46, v10, s28
	v_and_or_b32 v5, v10, s29, v5
	v_lshl_add_u64 v[48:49], v[12:13], 0, v[78:79]
	global_store_dwordx4 v[48:49], v[2:5], off
	v_bfe_u32 v10, v47, 16, 1
	v_add3_u32 v22, v47, v10, s28
	v_bfe_u32 v2, v11, 16, 1
	v_add3_u32 v2, v11, v2, s28
	v_bfe_u32 v3, v23, 16, 1
	v_lshrrev_b32_e32 v2, 16, v2
	v_add3_u32 v3, v23, v3, s28
	v_and_or_b32 v2, v3, s29, v2
	v_bfe_u32 v3, v25, 16, 1
	v_add3_u32 v3, v25, v3, s28
	v_bfe_u32 v4, v27, 16, 1
	v_lshrrev_b32_e32 v3, 16, v3
	v_add3_u32 v4, v27, v4, s28
	v_and_or_b32 v3, v4, s29, v3
	v_bfe_u32 v4, v29, 16, 1
	v_add3_u32 v4, v29, v4, s28
	v_bfe_u32 v5, v43, 16, 1
	v_lshrrev_b32_e32 v4, 16, v4
	v_add3_u32 v5, v43, v5, s28
	v_and_or_b32 v4, v5, s29, v4
	v_bfe_u32 v5, v45, 16, 1
	v_add3_u32 v5, v45, v5, s28
	v_lshrrev_b32_e32 v5, 16, v5
	ds_read2_b32 v[10:11], v94 offset0:16 offset1:24
	v_and_or_b32 v5, v22, s29, v5
	v_lshl_add_u64 v[22:23], v[12:13], 0, v[80:81]
	global_store_dwordx4 v[22:23], v[2:5], off
	ds_read2_b32 v[22:23], v94 offset0:49 offset1:57
	ds_read2_b32 v[24:25], v94 offset0:82 offset1:90
	ds_read2_b32 v[26:27], v94 offset0:115 offset1:123
	s_waitcnt lgkmcnt(3)
	v_bfe_u32 v2, v10, 16, 1
	v_add3_u32 v2, v10, v2, s28
	s_waitcnt lgkmcnt(2)
	v_bfe_u32 v3, v22, 16, 1
	ds_read2_b32 v[28:29], v94 offset0:148 offset1:156
	v_lshrrev_b32_e32 v2, 16, v2
	v_add3_u32 v3, v22, v3, s28
	ds_read2_b32 v[42:43], v94 offset0:181 offset1:189
	v_and_or_b32 v2, v3, s29, v2
	s_waitcnt lgkmcnt(3)
	v_bfe_u32 v3, v24, 16, 1
	v_add3_u32 v3, v24, v3, s28
	s_waitcnt lgkmcnt(2)
	v_bfe_u32 v4, v26, 16, 1
	ds_read2_b32 v[44:45], v94 offset0:214 offset1:222
	v_lshrrev_b32_e32 v3, 16, v3
	v_add3_u32 v4, v26, v4, s28
	ds_read2_b32 v[46:47], v94 offset0:247 offset1:255
	v_and_or_b32 v3, v4, s29, v3
	s_waitcnt lgkmcnt(3)
	v_bfe_u32 v4, v28, 16, 1
	v_add3_u32 v4, v28, v4, s28
	s_waitcnt lgkmcnt(2)
	v_bfe_u32 v5, v42, 16, 1
	v_lshrrev_b32_e32 v4, 16, v4
	v_add3_u32 v5, v42, v5, s28
	v_and_or_b32 v4, v5, s29, v4
	s_waitcnt lgkmcnt(1)
	v_bfe_u32 v5, v44, 16, 1
	v_add3_u32 v5, v44, v5, s28
	s_waitcnt lgkmcnt(0)
	v_bfe_u32 v10, v46, 16, 1
	v_lshrrev_b32_e32 v5, 16, v5
	v_add3_u32 v10, v46, v10, s28
	v_and_or_b32 v5, v10, s29, v5
	v_lshl_add_u64 v[48:49], v[12:13], 0, v[82:83]
	global_store_dwordx4 v[48:49], v[2:5], off
	v_bfe_u32 v10, v47, 16, 1
	v_add3_u32 v10, v47, v10, s28
	v_bfe_u32 v2, v11, 16, 1
	v_add3_u32 v2, v11, v2, s28
	v_bfe_u32 v3, v23, 16, 1
	v_lshrrev_b32_e32 v2, 16, v2
	v_add3_u32 v3, v23, v3, s28
	v_and_or_b32 v2, v3, s29, v2
	v_bfe_u32 v3, v25, 16, 1
	v_add3_u32 v3, v25, v3, s28
	v_bfe_u32 v4, v27, 16, 1
	v_lshrrev_b32_e32 v3, 16, v3
	v_add3_u32 v4, v27, v4, s28
	v_and_or_b32 v3, v4, s29, v3
	v_bfe_u32 v4, v29, 16, 1
	v_add3_u32 v4, v29, v4, s28
	v_bfe_u32 v5, v43, 16, 1
	v_lshrrev_b32_e32 v4, 16, v4
	v_add3_u32 v5, v43, v5, s28
	v_and_or_b32 v4, v5, s29, v4
	v_bfe_u32 v5, v45, 16, 1
	v_add3_u32 v5, v45, v5, s28
	v_lshrrev_b32_e32 v5, 16, v5
	v_and_or_b32 v5, v10, s29, v5
	v_lshl_add_u64 v[10:11], v[12:13], 0, v[84:85]
	global_store_dwordx4 v[10:11], v[2:5], off
	s_waitcnt lgkmcnt(0)
	s_add_i32 s31, s30, 7
	s_cmpk_lt_u32 s30, 0x3f9
	s_mov_b64 s[26:27], -1
	s_cbranch_scc1 .LBB0_615
	s_cmpk_lt_u32 s30, 0x7f9
	s_cbranch_scc1 .LBB0_612
	s_cmpk_lt_u32 s30, 0xff9
	s_mov_b64 s[18:19], -1
	s_cbranch_scc1 .LBB0_609
	s_add_i32 s6, s31, 0xf000
	s_and_b32 s7, s6, 0xffff
	s_mul_i32 s7, s7, 0xba2f
	s_lshr_b32 s15, s7, 24
	s_mul_i32 s7, s15, 0x160
	s_sub_i32 s18, s6, s7
	s_lshl_b32 s6, s18, 5
	s_and_b32 s7, s18, 0xffff
	s_add_i32 s14, s6, 0xea00
	s_cmpk_gt_u32 s7, 0xaf
	s_cselect_b32 s6, s14, s6
	s_sext_i32_i16 s7, s6
	s_cselect_b32 s14, 0x80, 0
	s_bfe_u32 s7, s7, 0x70018
	s_add_i32 s7, s6, s7
	s_sext_i32_i16 s19, s7
	s_and_b32 s7, s7, 0xff80
	s_sub_i32 s6, s6, s7
	s_lshl_b32 s19, s19, 1
	s_sext_i32_i16 s6, s6
	s_and_b32 s19, s19, 0xffffff00
	s_add_i32 s6, s14, s6
	s_add_i32 s14, s6, s19
	s_lshl_b32 s6, s15, 6
	s_mul_i32 s15, s15, 0x2c0000
	s_add_u32 s15, s84, s15
	s_addc_u32 s19, s85, 0
	s_lshl_b32 s18, s18, 7
	s_and_b32 s18, s18, 0x3ff80
	s_add_u32 s22, s15, s18
	s_mov_b32 s7, s1
	s_addc_u32 s23, s19, 0
	s_ashr_i32 s15, s14, 31
	s_mov_b64 s[18:19], 0

.LBB0_1059:
	s_add_i32 s0, s2, 0xffffe000
	s_cmpk_lt_i32 s2, 0x2000
	s_cselect_b32 s1, s3, 0
	s_cselect_b32 s0, s2, s0
	s_cselect_b32 s6, s77, s79
	s_cselect_b32 s7, s76, s78
	s_lshl_b64 s[0:1], s[0:1], 13
	s_add_u32 s0, s7, s0
	s_addc_u32 s1, s6, s1
	v_add_co_u32_e32 v4, vcc, s18, v158
	v_lshl_add_u64 v[2:3], s[0:1], 0, v[130:131]
	s_nop 0
	v_addc_co_u32_e32 v5, vcc, -1, v159, vcc
	v_add_co_u32_e32 v2, vcc, s19, v2
	global_load_dwordx4 v[126:129], v130, s[0:1] nt
	global_load_dwordx4 v[122:125], v130, s[0:1] offset:1024 nt
	global_load_dwordx2 v[52:53], v[4:5], off offset:-3584 nt
	global_load_dwordx2 v[50:51], v[4:5], off offset:-3072 nt
	global_load_dwordx2 v[44:45], v[4:5], off offset:-2560 nt
	global_load_dwordx2 v[42:43], v[4:5], off offset:-2048 nt
	global_load_dwordx4 v[118:121], v130, s[0:1] offset:2048 nt
	s_waitcnt lgkmcnt(0)
	global_load_dwordx4 v[114:117], v130, s[0:1] offset:3072 nt
	v_addc_co_u32_e32 v3, vcc, 0, v3, vcc
	global_load_dwordx4 v[110:113], v[2:3], off nt
	global_load_dwordx4 v[106:109], v[2:3], off offset:1024 nt
	global_load_dwordx2 v[40:41], v[4:5], off offset:-1536 nt
	global_load_dwordx2 v[38:39], v[4:5], off offset:-1024 nt
	global_load_dwordx2 v[36:37], v[4:5], off offset:-512 nt
	global_load_dwordx2 v[34:35], v[4:5], off nt
	global_load_dwordx4 v[102:105], v[2:3], off offset:2048 nt
	global_load_dwordx4 v[98:101], v[2:3], off offset:3072 nt
	s_add_i32 s12, s16, s2
	s_cmpk_lt_i32 s12, 0x2040
	s_cselect_b64 s[14:15], -1, 0
	s_cmpk_gt_i32 s12, 0x203f
	s_cbranch_scc1 .LBB0_1061
	s_ashr_i32 s13, s12, 31
	s_lshl_b64 s[0:1], s[12:13], 12
	v_lshl_add_u64 v[2:3], v[152:153], 0, s[0:1]
	s_add_i32 s0, s12, 0xffffe000
	s_cmpk_lt_i32 s12, 0x2000
	s_cselect_b32 s1, s13, 0
	s_cselect_b32 s0, s12, s0
	s_cselect_b32 s6, s77, s79
	s_cselect_b32 s7, s76, s78
	s_lshl_b64 s[0:1], s[0:1], 13
	s_add_u32 s0, s7, s0
	s_addc_u32 s1, s6, s1
	v_lshl_add_u64 v[4:5], s[0:1], 0, v[130:131]
	v_add_co_u32_e32 v4, vcc, s19, v4
	global_load_dwordx4 v[94:97], v130, s[0:1] nt
	global_load_dwordx4 v[90:93], v130, s[0:1] offset:1024 nt
	global_load_dwordx2 v[190:191], v[2:3], off nt
	global_load_dwordx2 v[188:189], v[2:3], off offset:512 nt
	global_load_dwordx2 v[186:187], v[2:3], off offset:1024 nt
	global_load_dwordx2 v[184:185], v[2:3], off offset:1536 nt
	global_load_dwordx4 v[86:89], v130, s[0:1] offset:2048 nt
	global_load_dwordx4 v[82:85], v130, s[0:1] offset:3072 nt
	v_addc_co_u32_e32 v5, vcc, 0, v5, vcc
	global_load_dwordx4 v[78:81], v[4:5], off nt
	global_load_dwordx4 v[74:77], v[4:5], off offset:1024 nt
	global_load_dwordx2 v[182:183], v[2:3], off offset:2048 nt
	global_load_dwordx2 v[180:181], v[2:3], off offset:2560 nt
	global_load_dwordx2 v[178:179], v[2:3], off offset:3072 nt
	global_load_dwordx2 v[176:177], v[2:3], off offset:3584 nt
	global_load_dwordx4 v[70:73], v[4:5], off offset:2048 nt
	global_load_dwordx4 v[66:69], v[4:5], off offset:3072 nt
.LBB0_1061:
	s_add_i32 s6, s17, s2
	s_cmpk_lt_i32 s6, 0x2040
	s_cselect_b64 s[10:11], -1, 0
	s_cmpk_gt_i32 s6, 0x203f
	s_cbranch_scc1 .LBB0_1063
	s_ashr_i32 s7, s6, 31
	s_lshl_b64 s[0:1], s[6:7], 12
	v_lshl_add_u64 v[2:3], v[152:153], 0, s[0:1]
	s_add_i32 s0, s6, 0xffffe000
	s_cmpk_lt_i32 s6, 0x2000
	s_cselect_b32 s1, s7, 0
	s_cselect_b32 s0, s6, s0
	s_cselect_b32 s7, s77, s79
	s_cselect_b32 s13, s76, s78
	s_lshl_b64 s[0:1], s[0:1], 13
	s_add_u32 s0, s13, s0
	s_addc_u32 s1, s7, s1
	v_lshl_add_u64 v[4:5], s[0:1], 0, v[130:131]
	v_add_co_u32_e32 v4, vcc, s19, v4
	global_load_dwordx4 v[30:33], v130, s[0:1] nt
	global_load_dwordx4 v[26:29], v130, s[0:1] offset:1024 nt
	global_load_dwordx2 v[172:173], v[2:3], off nt
	global_load_dwordx2 v[174:175], v[2:3], off offset:512 nt
	global_load_dwordx2 v[166:167], v[2:3], off offset:1024 nt
	global_load_dwordx2 v[164:165], v[2:3], off offset:1536 nt
	global_load_dwordx4 v[22:25], v130, s[0:1] offset:2048 nt
	global_load_dwordx4 v[18:21], v130, s[0:1] offset:3072 nt
	v_addc_co_u32_e32 v5, vcc, 0, v5, vcc
	global_load_dwordx4 v[14:17], v[4:5], off nt
	global_load_dwordx4 v[10:13], v[4:5], off offset:1024 nt
	global_load_dwordx2 v[170:171], v[2:3], off offset:2048 nt
	global_load_dwordx2 v[168:169], v[2:3], off offset:2560 nt
	global_load_dwordx2 v[162:163], v[2:3], off offset:3072 nt
	global_load_dwordx2 v[160:161], v[2:3], off offset:3584 nt
	global_load_dwordx4 v[6:9], v[4:5], off offset:2048 nt
	s_nop 0
	global_load_dwordx4 v[2:5], v[4:5], off offset:3072 nt

.LBB0_1293:
	s_ashr_i32 s1, s0, 31
	s_lshl_b64 s[2:3], s[0:1], 12
	v_lshl_add_u64 v[18:19], v[14:15], 0, s[2:3]
	v_lshl_add_u64 v[20:21], v[16:17], 0, s[2:3]
	global_load_dwordx2 v[96:97], v[18:19], off nt
	global_load_dwordx2 v[94:95], v[18:19], off offset:512 nt
	global_load_dwordx2 v[92:93], v[18:19], off offset:1024 nt
	global_load_dwordx2 v[88:89], v[18:19], off offset:1536 nt
	global_load_dwordx2 v[80:81], v[20:21], off nt
	global_load_dwordx2 v[78:79], v[20:21], off offset:512 nt
	global_load_dwordx2 v[76:77], v[20:21], off offset:1024 nt
	global_load_dwordx2 v[74:75], v[20:21], off offset:1536 nt
	global_load_dwordx2 v[90:91], v[18:19], off offset:2048 nt
	global_load_dwordx2 v[86:87], v[18:19], off offset:2560 nt
	global_load_dwordx2 v[82:83], v[18:19], off offset:3072 nt
	global_load_dwordx2 v[84:85], v[18:19], off offset:3584 nt
	global_load_dwordx2 v[72:73], v[20:21], off offset:2048 nt
	global_load_dwordx2 v[70:71], v[20:21], off offset:2560 nt
	global_load_dwordx2 v[68:69], v[20:21], off offset:3072 nt
	global_load_dwordx2 v[66:67], v[20:21], off offset:3584 nt
	s_add_i32 s2, s0, s6
	s_cmpk_lt_i32 s2, 0x2040
	s_cselect_b64 s[4:5], -1, 0
	s_cmpk_gt_i32 s2, 0x203f
	s_cbranch_scc1 .LBB0_1295
	s_ashr_i32 s3, s2, 31
	s_lshl_b64 s[10:11], s[2:3], 12
	v_lshl_add_u64 v[22:23], v[14:15], 0, s[10:11]
	global_load_dwordx2 v[24:25], v[22:23], off nt
	global_load_dwordx2 v[28:29], v[22:23], off offset:512 nt
	global_load_dwordx2 v[30:31], v[22:23], off offset:1024 nt
	global_load_dwordx2 v[34:35], v[22:23], off offset:1536 nt
	global_load_dwordx2 v[36:37], v[22:23], off offset:2048 nt
	global_load_dwordx2 v[98:99], v[22:23], off offset:2560 nt
	v_lshl_add_u64 v[40:41], v[16:17], 0, s[10:11]
	global_load_dwordx2 v[100:101], v[22:23], off offset:3072 nt
	global_load_dwordx2 v[56:57], v[40:41], off nt
	global_load_dwordx2 v[50:51], v[40:41], off offset:512 nt
	global_load_dwordx2 v[44:45], v[40:41], off offset:1024 nt
	global_load_dwordx2 v[38:39], v[40:41], off offset:1536 nt
	global_load_dwordx2 v[102:103], v[22:23], off offset:3584 nt
	global_load_dwordx2 v[32:33], v[40:41], off offset:2048 nt
	global_load_dwordx2 v[26:27], v[40:41], off offset:2560 nt
	global_load_dwordx2 v[20:21], v[40:41], off offset:3072 nt
	global_load_dwordx2 v[18:19], v[40:41], off offset:3584 nt
	s_waitcnt vmcnt(0)
	v_lshlrev_b32_e32 v62, 16, v24
	v_and_b32_e32 v63, 0xffff0000, v24
	v_lshlrev_b32_e32 v64, 16, v25
	v_and_b32_e32 v65, 0xffff0000, v25
	v_lshlrev_b32_e32 v58, 16, v28
	v_and_b32_e32 v59, 0xffff0000, v28
	v_lshlrev_b32_e32 v60, 16, v29
	v_and_b32_e32 v61, 0xffff0000, v29
	v_lshlrev_b32_e32 v52, 16, v30
	v_and_b32_e32 v53, 0xffff0000, v30
	v_lshlrev_b32_e32 v54, 16, v31
	v_and_b32_e32 v55, 0xffff0000, v31
	v_lshlrev_b32_e32 v46, 16, v34
	v_and_b32_e32 v47, 0xffff0000, v34
	v_lshlrev_b32_e32 v48, 16, v35
	v_and_b32_e32 v49, 0xffff0000, v35
	v_lshlrev_b32_e32 v40, 16, v36
	v_and_b32_e32 v41, 0xffff0000, v36
	v_lshlrev_b32_e32 v42, 16, v37
	v_and_b32_e32 v43, 0xffff0000, v37
	v_lshlrev_b32_e32 v34, 16, v98
	v_and_b32_e32 v35, 0xffff0000, v98
	v_lshlrev_b32_e32 v36, 16, v99
	v_and_b32_e32 v37, 0xffff0000, v99
	v_lshlrev_b32_e32 v28, 16, v100
	v_and_b32_e32 v29, 0xffff0000, v100
	v_lshlrev_b32_e32 v30, 16, v101
	v_and_b32_e32 v31, 0xffff0000, v101
	v_lshlrev_b32_e32 v22, 16, v102
	v_and_b32_e32 v23, 0xffff0000, v102
	v_lshlrev_b32_e32 v24, 16, v103
	v_and_b32_e32 v25, 0xffff0000, v103
